# GEMM mainloops: removed the redundant second lgkmcnt(0) after each phase barrier
# speedup vs baseline: 1.0142x; 1.0142x over previous
; #define PG8_STAGE(bufoff, gbase, voff) do { _Pragma("unroll") for (int _i = 0; _i < 2; ++_i) \
;         __builtin_amdgcn_global_load_lds((const unsigned*)((const char*)(gbase) + (voff)[_i]), (LAS unsigned*)(lds + (bufoff) + ldsw + _i * 8192), 16, 0, 0); } while (0)
; #define PG8_LDA(dst, b, h) do { _Pragma("unroll") for (int m = 0; m < 4; ++m) _Pragma("unroll") for (int k = 0; k < 2; ++k) dst[m][k] = *(const LAS bf16x8*)(lds + PG8_SA(b, h) + aoff + m * 2048 + k * 1024); } while (0)
; #define PG8_LDB(dst, b, h) do { _Pragma("unroll") for (int n = 0; n < 2; ++n) _Pragma("unroll") for (int k = 0; k < 2; ++k) dst[n][k] = *(const LAS bf16x8*)(lds + PG8_SB(b, h) + boff + n * 2048 + k * 1024); } while (0)
; #define PG8_MMA(ai, bj, At, Bt) do { __builtin_amdgcn_s_setprio(1); _Pragma("unroll") for (int m = 0; m < 4; ++m) _Pragma("unroll") for (int n = 0; n < 2; ++n) _Pragma("unroll") for (int k = 0; k < 2; ++k) \
;         acc[ai][bj][m][n] = __builtin_amdgcn_mfma_f32_16x16x32_bf16(Bt[n][k], At[m][k], acc[ai][bj][m][n], 0, 0, 0); __builtin_amdgcn_s_setprio(0); } while (0)
; #define PG8_WAIT_V(n) asm volatile("s_waitcnt vmcnt(" #n ")" ::: "memory")
; #define PG8_WAIT_L(n) asm volatile("s_waitcnt lgkmcnt(" #n ")" ::: "memory")
; #define PG8_BAR __builtin_amdgcn_s_barrier()
; #define PG8_SCHED __builtin_amdgcn_sched_barrier(0)
; template <class Epi, class Sched>
; __device__ __forceinline__ void gemm_phase(LAS unsigned char* lds, const Gemm g, const Sched S, const Epi E, const int tid) {
;     ...
;             PG8_LDB(B0, 0, 0); PG8_LDB(B1, 0, 1); PG8_SCHED; PG8_LDA(At, 0, 0); PG8_STAGE(PG8_SA(1, 1), a1 + hstepA, voffA);
;             PG8_WAIT_V(8); PG8_WAIT_L(0); PG8_BAR; PG8_MMA(0, 0, At, B0); PG8_MMA(0, 1, At, B1); PG8_BAR; PG8_SCHED;
;             PG8_LDA(At, 0, 1); PG8_STAGE(PG8_SB(0, 0), b2, voffB); PG8_STAGE(PG8_SB(0, 1), b2 + hstepB, voffB); PG8_STAGE(PG8_SA(0, 0), a2, voffA);
;             PG8_WAIT_V(8); PG8_WAIT_L(0); PG8_BAR; PG8_MMA(1, 0, At, B0); PG8_MMA(1, 1, At, B1); PG8_BAR; PG8_SCHED;
.LBB0_299:
	s_add_u32 s10, s22, 0xfffc0080
	s_addc_u32 s11, s23, -1
	s_add_i32 s44, 0, 0x10000
	s_cmp_eq_u32 vcc_hi, 28
	s_cselect_b32 s29, s93, s11
	s_cselect_b32 s28, s94, s10
	v_add_u32_e32 v154, s44, v167
	s_cselect_b32 s27, s95, vcc_lo
	s_cselect_b32 s26, s96, s97
	s_add_i32 s45, 0, 0x14000
	ds_read_b128 v[98:101], v154
	ds_read_b128 v[102:105], v154 offset:1024
	ds_read_b128 v[150:153], v154 offset:2048
	ds_read_b128 v[180:183], v154 offset:3072
	v_add_u32_e32 v154, s45, v167
	ds_read_b128 v[184:187], v154
	ds_read_b128 v[188:191], v154 offset:1024
	ds_read_b128 v[192:195], v154 offset:2048
	ds_read_b128 v[196:199], v154 offset:3072
	v_lshl_add_u64 v[154:155], s[22:23], 0, v[148:149]
	s_add_i32 m0, s47, 0xc000
	ds_read_b128 v[200:203], v179
	ds_read_b128 v[204:207], v179 offset:1024
	ds_read_b128 v[208:211], v179 offset:2048
	ds_read_b128 v[212:215], v179 offset:3072
	ds_read_b128 v[216:219], v179 offset:4096
	ds_read_b128 v[220:223], v179 offset:5120
	ds_read_b128 v[224:227], v179 offset:6144
	ds_read_b128 v[228:231], v179 offset:7168
	global_load_lds_dwordx4 v[154:155], off
	v_lshl_add_u64 v[154:155], s[22:23], 0, v[146:147]
	s_add_i32 m0, s47, 0xe000
	s_nop 0
	global_load_lds_dwordx4 v[154:155], off
	s_waitcnt vmcnt(8)
	s_waitcnt lgkmcnt(0)
	s_barrier
	s_setprio 1
	v_mfma_f32_16x16x32_bf16 v[134:137], v[98:101], v[200:203], v[134:137]
	v_mfma_f32_16x16x32_bf16 v[130:133], v[150:153], v[200:203], v[130:133]
	v_mfma_f32_16x16x32_bf16 v[126:129], v[98:101], v[208:211], v[126:129]
	v_mfma_f32_16x16x32_bf16 v[122:125], v[150:153], v[208:211], v[122:125]
	v_mfma_f32_16x16x32_bf16 v[118:121], v[98:101], v[216:219], v[118:121]
	v_mfma_f32_16x16x32_bf16 v[114:117], v[150:153], v[216:219], v[114:117]
	v_mfma_f32_16x16x32_bf16 v[110:113], v[98:101], v[224:227], v[110:113]
	v_mfma_f32_16x16x32_bf16 v[106:109], v[150:153], v[224:227], v[106:109]
	v_mfma_f32_16x16x32_bf16 v[134:137], v[102:105], v[204:207], v[134:137]
	v_mfma_f32_16x16x32_bf16 v[130:133], v[180:183], v[204:207], v[130:133]
	v_mfma_f32_16x16x32_bf16 v[126:129], v[102:105], v[212:215], v[126:129]
	v_mfma_f32_16x16x32_bf16 v[122:125], v[180:183], v[212:215], v[122:125]
	v_mfma_f32_16x16x32_bf16 v[118:121], v[102:105], v[220:223], v[118:121]
	v_mfma_f32_16x16x32_bf16 v[114:117], v[180:183], v[220:223], v[114:117]
	v_mfma_f32_16x16x32_bf16 v[110:113], v[102:105], v[228:231], v[110:113]
	v_mfma_f32_16x16x32_bf16 v[106:109], v[180:183], v[228:231], v[106:109]
	v_mfma_f32_16x16x32_bf16 v[62:65], v[184:187], v[200:203], v[62:65]
	v_mfma_f32_16x16x32_bf16 v[58:61], v[192:195], v[200:203], v[58:61]
	v_mfma_f32_16x16x32_bf16 v[54:57], v[184:187], v[208:211], v[54:57]
	v_mfma_f32_16x16x32_bf16 v[50:53], v[192:195], v[208:211], v[50:53]
	v_mfma_f32_16x16x32_bf16 v[46:49], v[184:187], v[216:219], v[46:49]
	v_mfma_f32_16x16x32_bf16 v[42:45], v[192:195], v[216:219], v[42:45]
	v_mfma_f32_16x16x32_bf16 v[38:41], v[184:187], v[224:227], v[38:41]
	v_mfma_f32_16x16x32_bf16 v[34:37], v[192:195], v[224:227], v[34:37]
	v_mfma_f32_16x16x32_bf16 v[62:65], v[188:191], v[204:207], v[62:65]
	v_mfma_f32_16x16x32_bf16 v[58:61], v[196:199], v[204:207], v[58:61]
	v_mfma_f32_16x16x32_bf16 v[54:57], v[188:191], v[212:215], v[54:57]
	v_mfma_f32_16x16x32_bf16 v[50:53], v[196:199], v[212:215], v[50:53]
	v_mfma_f32_16x16x32_bf16 v[46:49], v[188:191], v[220:223], v[46:49]
	v_mfma_f32_16x16x32_bf16 v[42:45], v[196:199], v[220:223], v[42:45]
	v_mfma_f32_16x16x32_bf16 v[38:41], v[188:191], v[228:231], v[38:41]
	v_mfma_f32_16x16x32_bf16 v[34:37], v[196:199], v[228:231], v[34:37]
	s_setprio 0
	s_barrier
	s_add_i32 s10, s44, s46
	v_lshl_add_u64 v[154:155], s[26:27], 0, v[142:143]
	s_mov_b32 m0, s10
	ds_read_b128 v[200:203], v179 offset:16384
	ds_read_b128 v[204:207], v179 offset:17408
	ds_read_b128 v[208:211], v179 offset:18432
	ds_read_b128 v[212:215], v179 offset:19456
	ds_read_b128 v[216:219], v179 offset:20480
	ds_read_b128 v[220:223], v179 offset:21504
	ds_read_b128 v[224:227], v179 offset:22528
	ds_read_b128 v[228:231], v179 offset:23552
	global_load_lds_dwordx4 v[154:155], off
	s_add_i32 m0, s10, 0x2000
	s_add_u32 s10, s26, 0x80000
	v_lshl_add_u64 v[232:233], s[26:27], 0, v[138:139]
	s_addc_u32 s11, s27, 0
	s_add_i32 s45, s45, s46
	global_load_lds_dwordx4 v[232:233], off
	v_lshl_add_u64 v[234:235], s[10:11], 0, v[142:143]
	s_mov_b32 m0, s45
	v_lshl_add_u64 v[246:247], s[28:29], 0, v[140:141]
	global_load_lds_dwordx4 v[234:235], off
	v_lshl_add_u64 v[234:235], s[10:11], 0, v[138:139]
	s_add_i32 m0, s45, 0x2000
	s_nop 0
	global_load_lds_dwordx4 v[234:235], off
	v_lshl_add_u64 v[234:235], s[28:29], 0, v[144:145]
	s_mov_b32 m0, s47
	s_nop 0
	global_load_lds_dwordx4 v[234:235], off
	s_mov_b32 m0, s48
	s_nop 0
	global_load_lds_dwordx4 v[246:247], off
	s_waitcnt vmcnt(8)
	s_waitcnt lgkmcnt(0)
	s_barrier
; #define PG8_STAGE(bufoff, gbase, voff) do { _Pragma("unroll") for (int _i = 0; _i < 2; ++_i) \
;         __builtin_amdgcn_global_load_lds((const unsigned*)((const char*)(gbase) + (voff)[_i]), (LAS unsigned*)(lds + (bufoff) + ldsw + _i * 8192), 16, 0, 0); } while (0)
; #define PG8_LDA(dst, b, h) do { _Pragma("unroll") for (int m = 0; m < 4; ++m) _Pragma("unroll") for (int k = 0; k < 2; ++k) dst[m][k] = *(const LAS bf16x8*)(lds + PG8_SA(b, h) + aoff + m * 2048 + k * 1024); } while (0)
; #define PG8_LDB(dst, b, h) do { _Pragma("unroll") for (int n = 0; n < 2; ++n) _Pragma("unroll") for (int k = 0; k < 2; ++k) dst[n][k] = *(const LAS bf16x8*)(lds + PG8_SB(b, h) + boff + n * 2048 + k * 1024); } while (0)
; #define PG8_MMA(ai, bj, At, Bt) do { __builtin_amdgcn_s_setprio(1); _Pragma("unroll") for (int m = 0; m < 4; ++m) _Pragma("unroll") for (int n = 0; n < 2; ++n) _Pragma("unroll") for (int k = 0; k < 2; ++k) \
;         acc[ai][bj][m][n] = __builtin_amdgcn_mfma_f32_16x16x32_bf16(Bt[n][k], At[m][k], acc[ai][bj][m][n], 0, 0, 0); __builtin_amdgcn_s_setprio(0); } while (0)
; #define PG8_WAIT_V(n) asm volatile("s_waitcnt vmcnt(" #n ")" ::: "memory")
; #define PG8_WAIT_L(n) asm volatile("s_waitcnt lgkmcnt(" #n ")" ::: "memory")
; #define PG8_BAR __builtin_amdgcn_s_barrier()
; #define PG8_SCHED __builtin_amdgcn_sched_barrier(0)
; template <class Epi, class Sched>
; __device__ __forceinline__ void gemm_phase(LAS unsigned char* lds, const Gemm g, const Sched S, const Epi E, const int tid) {
;     ...
;             PG8_WAIT_V(8); PG8_WAIT_L(0); PG8_BAR; PG8_MMA(1, 0, At, B0); PG8_MMA(1, 1, At, B1); PG8_BAR; PG8_SCHED;
;             PG8_LDB(B0, 1, 0); PG8_LDB(B1, 1, 1); PG8_SCHED; PG8_LDA(At, 1, 0); PG8_STAGE(PG8_SA(0, 1), a2 + hstepA, voffA);
;             PG8_WAIT_V(8); PG8_WAIT_L(0); PG8_BAR; PG8_MMA(0, 0, At, B0); PG8_MMA(0, 1, At, B1); PG8_BAR; PG8_SCHED;
	s_setprio 1
	v_mfma_f32_16x16x32_bf16 v[94:97], v[98:101], v[200:203], v[94:97]
	v_mfma_f32_16x16x32_bf16 v[90:93], v[150:153], v[200:203], v[90:93]
	v_mfma_f32_16x16x32_bf16 v[86:89], v[98:101], v[208:211], v[86:89]
	v_mfma_f32_16x16x32_bf16 v[82:85], v[150:153], v[208:211], v[82:85]
	v_mfma_f32_16x16x32_bf16 v[78:81], v[98:101], v[216:219], v[78:81]
	v_mfma_f32_16x16x32_bf16 v[74:77], v[150:153], v[216:219], v[74:77]
	v_mfma_f32_16x16x32_bf16 v[70:73], v[98:101], v[224:227], v[70:73]
	v_mfma_f32_16x16x32_bf16 v[66:69], v[150:153], v[224:227], v[66:69]
	v_mfma_f32_16x16x32_bf16 v[94:97], v[102:105], v[204:207], v[94:97]
	v_mfma_f32_16x16x32_bf16 v[90:93], v[180:183], v[204:207], v[90:93]
	v_mfma_f32_16x16x32_bf16 v[86:89], v[102:105], v[212:215], v[86:89]
	v_mfma_f32_16x16x32_bf16 v[82:85], v[180:183], v[212:215], v[82:85]
	v_mfma_f32_16x16x32_bf16 v[78:81], v[102:105], v[220:223], v[78:81]
	v_mfma_f32_16x16x32_bf16 v[74:77], v[180:183], v[220:223], v[74:77]
	v_mfma_f32_16x16x32_bf16 v[70:73], v[102:105], v[228:231], v[70:73]
	v_mfma_f32_16x16x32_bf16 v[66:69], v[180:183], v[228:231], v[66:69]
	v_mfma_f32_16x16x32_bf16 v[30:33], v[184:187], v[200:203], v[30:33]
	v_mfma_f32_16x16x32_bf16 v[26:29], v[192:195], v[200:203], v[26:29]
	v_mfma_f32_16x16x32_bf16 v[22:25], v[184:187], v[208:211], v[22:25]
	v_mfma_f32_16x16x32_bf16 v[18:21], v[192:195], v[208:211], v[18:21]
	v_mfma_f32_16x16x32_bf16 v[14:17], v[184:187], v[216:219], v[14:17]
	v_mfma_f32_16x16x32_bf16 v[10:13], v[192:195], v[216:219], v[10:13]
	v_mfma_f32_16x16x32_bf16 v[6:9], v[184:187], v[224:227], v[6:9]
	v_mfma_f32_16x16x32_bf16 v[2:5], v[192:195], v[224:227], v[2:5]
	v_mfma_f32_16x16x32_bf16 v[30:33], v[188:191], v[204:207], v[30:33]
	v_mfma_f32_16x16x32_bf16 v[26:29], v[196:199], v[204:207], v[26:29]
	v_mfma_f32_16x16x32_bf16 v[22:25], v[188:191], v[212:215], v[22:25]
	v_mfma_f32_16x16x32_bf16 v[18:21], v[196:199], v[212:215], v[18:21]
	v_mfma_f32_16x16x32_bf16 v[14:17], v[188:191], v[220:223], v[14:17]
	v_mfma_f32_16x16x32_bf16 v[10:13], v[196:199], v[220:223], v[10:13]
	v_mfma_f32_16x16x32_bf16 v[6:9], v[188:191], v[228:231], v[6:9]
	v_mfma_f32_16x16x32_bf16 v[2:5], v[196:199], v[228:231], v[2:5]
	s_setprio 0
	s_barrier
	s_add_i32 s45, 0, 0x18000
	s_add_i32 s6, 0, 0x1c000
	v_add_u32_e32 v180, s45, v167
	v_add_u32_e32 v196, s6, v167
	ds_read_b128 v[98:101], v180
	ds_read_b128 v[102:105], v180 offset:1024
	ds_read_b128 v[150:153], v180 offset:2048
	ds_read_b128 v[180:183], v180 offset:3072
	ds_read_b128 v[184:187], v196
	ds_read_b128 v[188:191], v196 offset:1024
	ds_read_b128 v[192:195], v196 offset:2048
	ds_read_b128 v[196:199], v196 offset:3072
	s_add_u32 s10, s28, 0x40000
	s_addc_u32 s11, s29, 0
	s_mov_b32 m0, s49
	v_lshl_add_u64 v[248:249], s[10:11], 0, v[144:145]
	ds_read_b128 v[200:203], v179 offset:32768
	ds_read_b128 v[204:207], v179 offset:33792
	ds_read_b128 v[208:211], v179 offset:34816
	ds_read_b128 v[212:215], v179 offset:35840
	ds_read_b128 v[216:219], v179 offset:36864
	ds_read_b128 v[220:223], v179 offset:37888
	ds_read_b128 v[224:227], v179 offset:38912
	ds_read_b128 v[228:231], v179 offset:39936
	global_load_lds_dwordx4 v[248:249], off
	v_lshl_add_u64 v[248:249], s[10:11], 0, v[140:141]
	s_mov_b32 m0, s62
	s_nop 0
	global_load_lds_dwordx4 v[248:249], off
	s_waitcnt vmcnt(8)
	s_waitcnt lgkmcnt(0)
	s_barrier
	s_setprio 1
	v_mfma_f32_16x16x32_bf16 v[134:137], v[98:101], v[200:203], v[134:137]
	v_mfma_f32_16x16x32_bf16 v[130:133], v[150:153], v[200:203], v[130:133]
	v_mfma_f32_16x16x32_bf16 v[126:129], v[98:101], v[208:211], v[126:129]
	v_mfma_f32_16x16x32_bf16 v[122:125], v[150:153], v[208:211], v[122:125]
	v_mfma_f32_16x16x32_bf16 v[118:121], v[98:101], v[216:219], v[118:121]
	v_mfma_f32_16x16x32_bf16 v[114:117], v[150:153], v[216:219], v[114:117]
	v_mfma_f32_16x16x32_bf16 v[110:113], v[98:101], v[224:227], v[110:113]
	v_mfma_f32_16x16x32_bf16 v[106:109], v[150:153], v[224:227], v[106:109]
	v_mfma_f32_16x16x32_bf16 v[134:137], v[102:105], v[204:207], v[134:137]
	v_mfma_f32_16x16x32_bf16 v[130:133], v[180:183], v[204:207], v[130:133]
	v_mfma_f32_16x16x32_bf16 v[126:129], v[102:105], v[212:215], v[126:129]
	v_mfma_f32_16x16x32_bf16 v[122:125], v[180:183], v[212:215], v[122:125]
	v_mfma_f32_16x16x32_bf16 v[118:121], v[102:105], v[220:223], v[118:121]
	v_mfma_f32_16x16x32_bf16 v[114:117], v[180:183], v[220:223], v[114:117]
	v_mfma_f32_16x16x32_bf16 v[110:113], v[102:105], v[228:231], v[110:113]
	v_mfma_f32_16x16x32_bf16 v[106:109], v[180:183], v[228:231], v[106:109]
	v_mfma_f32_16x16x32_bf16 v[62:65], v[184:187], v[200:203], v[62:65]
	v_mfma_f32_16x16x32_bf16 v[58:61], v[192:195], v[200:203], v[58:61]
	v_mfma_f32_16x16x32_bf16 v[54:57], v[184:187], v[208:211], v[54:57]
	v_mfma_f32_16x16x32_bf16 v[50:53], v[192:195], v[208:211], v[50:53]
	v_mfma_f32_16x16x32_bf16 v[46:49], v[184:187], v[216:219], v[46:49]
	v_mfma_f32_16x16x32_bf16 v[42:45], v[192:195], v[216:219], v[42:45]
	v_mfma_f32_16x16x32_bf16 v[38:41], v[184:187], v[224:227], v[38:41]
	v_mfma_f32_16x16x32_bf16 v[34:37], v[192:195], v[224:227], v[34:37]
	v_mfma_f32_16x16x32_bf16 v[62:65], v[188:191], v[204:207], v[62:65]
	v_mfma_f32_16x16x32_bf16 v[58:61], v[196:199], v[204:207], v[58:61]
	v_mfma_f32_16x16x32_bf16 v[54:57], v[188:191], v[212:215], v[54:57]
	v_mfma_f32_16x16x32_bf16 v[50:53], v[196:199], v[212:215], v[50:53]
	v_mfma_f32_16x16x32_bf16 v[46:49], v[188:191], v[220:223], v[46:49]
	v_mfma_f32_16x16x32_bf16 v[42:45], v[196:199], v[220:223], v[42:45]
	v_mfma_f32_16x16x32_bf16 v[38:41], v[188:191], v[228:231], v[38:41]
	v_mfma_f32_16x16x32_bf16 v[34:37], v[196:199], v[228:231], v[34:37]
	s_setprio 0
	s_barrier
; #define PG8_STAGE(bufoff, gbase, voff) do { _Pragma("unroll") for (int _i = 0; _i < 2; ++_i) \
;         __builtin_amdgcn_global_load_lds((const unsigned*)((const char*)(gbase) + (voff)[_i]), (LAS unsigned*)(lds + (bufoff) + ldsw + _i * 8192), 16, 0, 0); } while (0)
; #define PG8_LDA(dst, b, h) do { _Pragma("unroll") for (int m = 0; m < 4; ++m) _Pragma("unroll") for (int k = 0; k < 2; ++k) dst[m][k] = *(const LAS bf16x8*)(lds + PG8_SA(b, h) + aoff + m * 2048 + k * 1024); } while (0)
; #define PG8_MMA(ai, bj, At, Bt) do { __builtin_amdgcn_s_setprio(1); _Pragma("unroll") for (int m = 0; m < 4; ++m) _Pragma("unroll") for (int n = 0; n < 2; ++n) _Pragma("unroll") for (int k = 0; k < 2; ++k) \
;         acc[ai][bj][m][n] = __builtin_amdgcn_mfma_f32_16x16x32_bf16(Bt[n][k], At[m][k], acc[ai][bj][m][n], 0, 0, 0); __builtin_amdgcn_s_setprio(0); } while (0)
; #define PG8_WAIT_V(n) asm volatile("s_waitcnt vmcnt(" #n ")" ::: "memory")
; #define PG8_WAIT_L(n) asm volatile("s_waitcnt lgkmcnt(" #n ")" ::: "memory")
; #define PG8_BAR __builtin_amdgcn_s_barrier()
; #define PG8_SCHED __builtin_amdgcn_sched_barrier(0)
; template <class Epi, class Sched>
; __device__ __forceinline__ void gemm_phase(LAS unsigned char* lds, const Gemm g, const Sched S, const Epi E, const int tid) {
;     ...
;             PG8_WAIT_V(8); PG8_WAIT_L(0); PG8_BAR; PG8_MMA(0, 0, At, B0); PG8_MMA(0, 1, At, B1); PG8_BAR; PG8_SCHED;
;             PG8_LDA(At, 1, 1); PG8_STAGE(PG8_SB(1, 0), b3, voffB); PG8_STAGE(PG8_SB(1, 1), b3 + hstepB, voffB); PG8_STAGE(PG8_SA(1, 0), a3, voffA);
;             PG8_WAIT_V(8); PG8_WAIT_L(0); PG8_BAR; PG8_MMA(1, 0, At, B0); PG8_MMA(1, 1, At, B1); PG8_BAR; PG8_SCHED;
;         }
	s_add_i32 s7, s45, s46
	v_lshl_add_u64 v[154:155], v[154:155], 0, s[64:65]
	s_mov_b32 m0, s7
	ds_read_b128 v[200:203], v179 offset:49152
	ds_read_b128 v[204:207], v179 offset:50176
	ds_read_b128 v[208:211], v179 offset:51200
	ds_read_b128 v[212:215], v179 offset:52224
	ds_read_b128 v[216:219], v179 offset:53248
	ds_read_b128 v[220:223], v179 offset:54272
	ds_read_b128 v[224:227], v179 offset:55296
	ds_read_b128 v[228:231], v179 offset:56320
	global_load_lds_dwordx4 v[154:155], off
	s_add_i32 m0, s7, 0x2000
	s_add_u32 s10, s26, 0x80080
	v_lshl_add_u64 v[154:155], v[232:233], 0, s[64:65]
	s_addc_u32 s11, s27, 0
	s_add_i32 s6, s6, s46
	global_load_lds_dwordx4 v[154:155], off
	v_lshl_add_u64 v[154:155], s[10:11], 0, v[142:143]
	s_mov_b32 m0, s6
	s_nop 0
	global_load_lds_dwordx4 v[154:155], off
	v_lshl_add_u64 v[154:155], s[10:11], 0, v[138:139]
	s_add_i32 m0, s6, 0x2000
	s_nop 0
	global_load_lds_dwordx4 v[154:155], off
	v_lshl_add_u64 v[154:155], v[234:235], 0, s[64:65]
	s_mov_b32 m0, s84
	s_nop 0
	global_load_lds_dwordx4 v[154:155], off
	v_lshl_add_u64 v[154:155], v[246:247], 0, s[64:65]
	s_mov_b32 m0, s85
	s_nop 0
	global_load_lds_dwordx4 v[154:155], off
	s_waitcnt vmcnt(8)
	s_waitcnt lgkmcnt(0)
	s_barrier
	s_setprio 1
	v_mfma_f32_16x16x32_bf16 v[94:97], v[98:101], v[200:203], v[94:97]
	v_mfma_f32_16x16x32_bf16 v[90:93], v[150:153], v[200:203], v[90:93]
	v_mfma_f32_16x16x32_bf16 v[86:89], v[98:101], v[208:211], v[86:89]
	v_mfma_f32_16x16x32_bf16 v[82:85], v[150:153], v[208:211], v[82:85]
	v_mfma_f32_16x16x32_bf16 v[78:81], v[98:101], v[216:219], v[78:81]
	v_mfma_f32_16x16x32_bf16 v[74:77], v[150:153], v[216:219], v[74:77]
	v_mfma_f32_16x16x32_bf16 v[70:73], v[98:101], v[224:227], v[70:73]
	v_mfma_f32_16x16x32_bf16 v[66:69], v[150:153], v[224:227], v[66:69]
	v_mfma_f32_16x16x32_bf16 v[94:97], v[102:105], v[204:207], v[94:97]
	v_mfma_f32_16x16x32_bf16 v[90:93], v[180:183], v[204:207], v[90:93]
	v_mfma_f32_16x16x32_bf16 v[86:89], v[102:105], v[212:215], v[86:89]
	v_mfma_f32_16x16x32_bf16 v[82:85], v[180:183], v[212:215], v[82:85]
	v_mfma_f32_16x16x32_bf16 v[78:81], v[102:105], v[220:223], v[78:81]
	v_mfma_f32_16x16x32_bf16 v[74:77], v[180:183], v[220:223], v[74:77]
	v_mfma_f32_16x16x32_bf16 v[70:73], v[102:105], v[228:231], v[70:73]
	v_mfma_f32_16x16x32_bf16 v[66:69], v[180:183], v[228:231], v[66:69]
	v_mfma_f32_16x16x32_bf16 v[30:33], v[184:187], v[200:203], v[30:33]
	v_mfma_f32_16x16x32_bf16 v[26:29], v[192:195], v[200:203], v[26:29]
	v_mfma_f32_16x16x32_bf16 v[22:25], v[184:187], v[208:211], v[22:25]
	v_mfma_f32_16x16x32_bf16 v[18:21], v[192:195], v[208:211], v[18:21]
	v_mfma_f32_16x16x32_bf16 v[14:17], v[184:187], v[216:219], v[14:17]
	v_mfma_f32_16x16x32_bf16 v[10:13], v[192:195], v[216:219], v[10:13]
	v_mfma_f32_16x16x32_bf16 v[6:9], v[184:187], v[224:227], v[6:9]
	v_mfma_f32_16x16x32_bf16 v[2:5], v[192:195], v[224:227], v[2:5]
	v_mfma_f32_16x16x32_bf16 v[30:33], v[188:191], v[204:207], v[30:33]
	v_mfma_f32_16x16x32_bf16 v[26:29], v[196:199], v[204:207], v[26:29]
	v_mfma_f32_16x16x32_bf16 v[22:25], v[188:191], v[212:215], v[22:25]
	v_mfma_f32_16x16x32_bf16 v[18:21], v[196:199], v[212:215], v[18:21]
	v_mfma_f32_16x16x32_bf16 v[14:17], v[188:191], v[220:223], v[14:17]
	v_mfma_f32_16x16x32_bf16 v[10:13], v[196:199], v[220:223], v[10:13]
	v_mfma_f32_16x16x32_bf16 v[6:9], v[188:191], v[228:231], v[6:9]
	v_mfma_f32_16x16x32_bf16 v[2:5], v[196:199], v[228:231], v[2:5]
	s_setprio 0
	s_barrier
	s_add_i32 vcc_hi, vcc_hi, 2
	s_add_u32 s97, s97, 0x100
	s_addc_u32 vcc_lo, vcc_lo, 0
	s_add_u32 s22, s22, 0x100
	s_addc_u32 s23, s23, 0
	s_cmp_gt_u32 vcc_hi, 29
	s_cbranch_scc0 .LBB0_299
	s_and_b64 vcc, exec, s[18:19]
	s_cbranch_vccz .LBB0_302
	s_barrier

; #define PG8_STAGE(bufoff, gbase, voff) do { _Pragma("unroll") for (int _i = 0; _i < 2; ++_i) \
;         __builtin_amdgcn_global_load_lds((const unsigned*)((const char*)(gbase) + (voff)[_i]), (LAS unsigned*)(lds + (bufoff) + ldsw + _i * 8192), 16, 0, 0); } while (0)
; #define PG8_LDA(dst, b, h) do { _Pragma("unroll") for (int m = 0; m < 4; ++m) _Pragma("unroll") for (int k = 0; k < 2; ++k) dst[m][k] = *(const LAS bf16x8*)(lds + PG8_SA(b, h) + aoff + m * 2048 + k * 1024); } while (0)
; #define PG8_LDB(dst, b, h) do { _Pragma("unroll") for (int n = 0; n < 2; ++n) _Pragma("unroll") for (int k = 0; k < 2; ++k) dst[n][k] = *(const LAS bf16x8*)(lds + PG8_SB(b, h) + boff + n * 2048 + k * 1024); } while (0)
; #define PG8_MMA(ai, bj, At, Bt) do { __builtin_amdgcn_s_setprio(1); _Pragma("unroll") for (int m = 0; m < 4; ++m) _Pragma("unroll") for (int n = 0; n < 2; ++n) _Pragma("unroll") for (int k = 0; k < 2; ++k) \
;         acc[ai][bj][m][n] = __builtin_amdgcn_mfma_f32_16x16x32_bf16(Bt[n][k], At[m][k], acc[ai][bj][m][n], 0, 0, 0); __builtin_amdgcn_s_setprio(0); } while (0)
; template <class Epi, class Sched>
; __device__ __forceinline__ void gemm_phase(LAS unsigned char* lds, const Gemm g, const Sched S, const Epi E, const int tid) {
;     ...
;         for (int t = 0; t < nt; t += 2) {
;             const bool last = (t == nt - 2);
;             const char* a1 = cA + (size_t)(t + 1) * kstep;
;             const char* a2 = last ? nA : cA + (size_t)(t + 2) * kstep; const char* b2 = last ? nB : cB + (size_t)(t + 2) * kstep;
;             const char* a3 = a2 + kstep; const char* b3 = b2 + kstep;
;             PG8_LDB(B0, 0, 0); PG8_LDB(B1, 0, 1); PG8_SCHED; PG8_LDA(At, 0, 0); PG8_STAGE(PG8_SA(1, 1), a1 + hstepA, voffA);
;             PG8_WAIT_V(8); PG8_WAIT_L(0); PG8_BAR; PG8_MMA(0, 0, At, B0); PG8_MMA(0, 1, At, B1); PG8_BAR; PG8_SCHED;
;             PG8_LDA(At, 0, 1); PG8_STAGE(PG8_SB(0, 0), b2, voffB); PG8_STAGE(PG8_SB(0, 1), b2 + hstepB, voffB); PG8_STAGE(PG8_SA(0, 0), a2, voffA);
;             PG8_WAIT_V(8); PG8_WAIT_L(0); PG8_BAR; PG8_MMA(1, 0, At, B0); PG8_MMA(1, 1, At, B1); PG8_BAR; PG8_SCHED;
;             PG8_LDB(B0, 1, 0); PG8_LDB(B1, 1, 1); PG8_SCHED; PG8_LDA(At, 1, 0); PG8_STAGE(PG8_SA(0, 1), a2 + hstepA, voffA);
;             PG8_WAIT_V(8); PG8_WAIT_L(0); PG8_BAR; PG8_MMA(0, 0, At, B0); PG8_MMA(0, 1, At, B1); PG8_BAR; PG8_SCHED;
.LBB0_310:
	s_mov_b32 s6, s92
	s_ashr_i32 s92, s89, 4
	s_cmp_lt_i32 s89, 32
	s_mov_b64 s[42:43], s[4:5]
	s_cselect_b64 s[4:5], -1, 0
	s_and_b64 s[4:5], s[4:5], exec
	s_cselect_b32 s4, s92, s6
	s_ashr_i32 s5, s4, 31
	s_lshl_b64 s[4:5], s[4:5], 17
	s_add_u32 s4, s25, s4
	s_addc_u32 s5, s46, s5
	s_cmp_lt_i32 s89, 32
	s_cselect_b64 s[10:11], -1, 0
	s_and_b64 s[10:11], s[10:11], exec
	s_cselect_b32 s10, s89, s93
	v_add_u32_e32 v130, s44, v70
	s_cselect_b32 s26, s4, s42
	s_cselect_b32 s27, s5, s43
	s_ashr_i32 s11, s10, 31
	ds_read_b128 v[2:5], v130
	ds_read_b128 v[6:9], v130 offset:1024
	ds_read_b128 v[10:13], v130 offset:2048
	ds_read_b128 v[14:17], v130 offset:3072
	s_lshl_b64 s[10:11], s[10:11], 17
	s_mov_b64 s[40:41], s[16:17]
	s_add_u32 s16, s8, s10
	s_addc_u32 s17, s9, s11
	s_cmp_lt_i32 s89, 32
	s_cselect_b64 s[22:23], -1, 0
	s_and_b64 s[10:11], s[22:23], exec
	s_cselect_b32 s29, s17, s41
	s_cselect_b32 s28, s16, s40
	s_add_u32 s10, s40, 0x10080
	s_addc_u32 s11, s41, 0
	s_add_i32 s97, s37, 0xc000
	v_lshl_add_u64 v[50:51], s[10:11], 0, v[68:69]
	s_mov_b32 m0, s97
	s_add_i32 s13, s37, 0xe000
	ds_read_b128 v[18:21], v71
	ds_read_b128 v[22:25], v71 offset:1024
	ds_read_b128 v[26:29], v71 offset:2048
	ds_read_b128 v[30:33], v71 offset:3072
	ds_read_b128 v[34:37], v71 offset:4096
	ds_read_b128 v[38:41], v71 offset:5120
	ds_read_b128 v[42:45], v71 offset:6144
	ds_read_b128 v[46:49], v71 offset:7168
	global_load_lds_dwordx4 v[50:51], off
	v_lshl_add_u64 v[50:51], s[10:11], 0, v[66:67]
	s_mov_b32 m0, s13
	s_nop 0
	global_load_lds_dwordx4 v[50:51], off
	s_waitcnt vmcnt(8)
	s_waitcnt lgkmcnt(0)
	s_barrier
	s_setprio 1
	v_mfma_f32_16x16x32_bf16 v[50:53], v[2:5], v[18:21], 0
	v_mfma_f32_16x16x32_bf16 v[18:21], v[10:13], v[18:21], 0
	v_mfma_f32_16x16x32_bf16 v[50:53], v[6:9], v[22:25], v[50:53]
	v_mfma_f32_16x16x32_bf16 v[18:21], v[14:17], v[22:25], v[18:21]
	v_mfma_f32_16x16x32_bf16 v[22:25], v[2:5], v[26:29], 0
	v_mfma_f32_16x16x32_bf16 v[26:29], v[10:13], v[26:29], 0
	v_mfma_f32_16x16x32_bf16 v[22:25], v[6:9], v[30:33], v[22:25]
	v_mfma_f32_16x16x32_bf16 v[26:29], v[14:17], v[30:33], v[26:29]
	v_mfma_f32_16x16x32_bf16 v[30:33], v[2:5], v[34:37], 0
	v_mfma_f32_16x16x32_bf16 v[34:37], v[10:13], v[34:37], 0
	v_mfma_f32_16x16x32_bf16 v[30:33], v[6:9], v[38:41], v[30:33]
	v_mfma_f32_16x16x32_bf16 v[34:37], v[14:17], v[38:41], v[34:37]
	v_mfma_f32_16x16x32_bf16 v[38:41], v[2:5], v[42:45], 0
	v_mfma_f32_16x16x32_bf16 v[42:45], v[10:13], v[42:45], 0
	v_mfma_f32_16x16x32_bf16 v[38:41], v[6:9], v[46:49], v[38:41]
	v_mfma_f32_16x16x32_bf16 v[42:45], v[14:17], v[46:49], v[42:45]
	s_setprio 0
	s_barrier
	s_add_i32 s96, s44, s47
	v_lshl_add_u64 v[120:121], s[42:43], 0, v[68:69]
	s_mov_b64 s[6:7], 0x100
	s_add_i32 s94, s96, 0x2000
	v_lshl_add_u64 v[88:89], v[120:121], 0, s[6:7]
	s_mov_b32 m0, s96
	v_lshl_add_u64 v[122:123], s[42:43], 0, v[66:67]
	s_add_u32 s10, s42, 0x10100
	ds_read_b128 v[46:49], v71 offset:16384
	ds_read_b128 v[54:57], v71 offset:17408
	ds_read_b128 v[58:61], v71 offset:18432
	ds_read_b128 v[62:65], v71 offset:19456
	ds_read_b128 v[72:75], v71 offset:20480
	ds_read_b128 v[76:79], v71 offset:21504
	ds_read_b128 v[80:83], v71 offset:22528
	ds_read_b128 v[84:87], v71 offset:23552
	global_load_lds_dwordx4 v[88:89], off
	v_lshl_add_u64 v[88:89], v[122:123], 0, s[6:7]
	s_mov_b32 m0, s94
	s_addc_u32 s11, s43, 0
	global_load_lds_dwordx4 v[88:89], off
	v_lshl_add_u64 v[88:89], s[10:11], 0, v[68:69]
	s_mov_b32 m0, s48
	v_lshl_add_u64 v[124:125], s[40:41], 0, v[68:69]
	global_load_lds_dwordx4 v[88:89], off
	v_lshl_add_u64 v[88:89], s[10:11], 0, v[66:67]
	s_mov_b32 m0, s49
	v_lshl_add_u64 v[126:127], s[40:41], 0, v[66:67]
	global_load_lds_dwordx4 v[88:89], off
	v_lshl_add_u64 v[88:89], v[124:125], 0, s[6:7]
	s_mov_b32 m0, s37
	s_nop 0
	global_load_lds_dwordx4 v[88:89], off
	v_lshl_add_u64 v[88:89], v[126:127], 0, s[6:7]
	s_mov_b32 m0, s62
	s_nop 0
	global_load_lds_dwordx4 v[88:89], off
	s_waitcnt vmcnt(8)
	s_waitcnt lgkmcnt(0)
	s_barrier
	s_setprio 1
	v_mfma_f32_16x16x32_bf16 v[88:91], v[2:5], v[46:49], 0
	v_mfma_f32_16x16x32_bf16 v[46:49], v[10:13], v[46:49], 0
	v_mfma_f32_16x16x32_bf16 v[88:91], v[6:9], v[54:57], v[88:91]
	v_mfma_f32_16x16x32_bf16 v[46:49], v[14:17], v[54:57], v[46:49]
	v_mfma_f32_16x16x32_bf16 v[54:57], v[2:5], v[58:61], 0
	v_mfma_f32_16x16x32_bf16 v[58:61], v[10:13], v[58:61], 0
	v_mfma_f32_16x16x32_bf16 v[54:57], v[6:9], v[62:65], v[54:57]
	v_mfma_f32_16x16x32_bf16 v[58:61], v[14:17], v[62:65], v[58:61]
	v_mfma_f32_16x16x32_bf16 v[62:65], v[2:5], v[72:75], 0
	v_mfma_f32_16x16x32_bf16 v[2:5], v[2:5], v[80:83], 0
	v_mfma_f32_16x16x32_bf16 v[62:65], v[6:9], v[76:79], v[62:65]
	v_mfma_f32_16x16x32_bf16 v[2:5], v[6:9], v[84:87], v[2:5]
	v_mfma_f32_16x16x32_bf16 v[6:9], v[10:13], v[80:83], 0
	v_mfma_f32_16x16x32_bf16 v[72:75], v[10:13], v[72:75], 0
	v_mfma_f32_16x16x32_bf16 v[6:9], v[14:17], v[84:87], v[6:9]
	v_mfma_f32_16x16x32_bf16 v[72:75], v[14:17], v[76:79], v[72:75]
	s_setprio 0
	s_barrier
	v_add_u32_e32 v131, s45, v70
	ds_read_b128 v[10:13], v131
	ds_read_b128 v[14:17], v131 offset:1024
	ds_read_b128 v[76:79], v131 offset:2048
	ds_read_b128 v[80:83], v131 offset:3072
	s_add_u32 s10, s40, 0x10100
	s_addc_u32 s11, s41, 0
	s_mov_b32 m0, s68
	v_lshl_add_u64 v[128:129], s[10:11], 0, v[68:69]
	ds_read_b128 v[84:87], v71 offset:32768
	ds_read_b128 v[92:95], v71 offset:33792
	ds_read_b128 v[96:99], v71 offset:34816
	ds_read_b128 v[100:103], v71 offset:35840
	ds_read_b128 v[104:107], v71 offset:36864
	ds_read_b128 v[108:111], v71 offset:37888
	ds_read_b128 v[112:115], v71 offset:38912
	ds_read_b128 v[116:119], v71 offset:39936
	global_load_lds_dwordx4 v[128:129], off
	v_lshl_add_u64 v[128:129], s[10:11], 0, v[66:67]
	s_mov_b32 m0, s69
	s_nop 0
	global_load_lds_dwordx4 v[128:129], off
	s_waitcnt vmcnt(8)
	s_waitcnt lgkmcnt(0)
	s_barrier
; #define PG8_STAGE(bufoff, gbase, voff) do { _Pragma("unroll") for (int _i = 0; _i < 2; ++_i) \
;         __builtin_amdgcn_global_load_lds((const unsigned*)((const char*)(gbase) + (voff)[_i]), (LAS unsigned*)(lds + (bufoff) + ldsw + _i * 8192), 16, 0, 0); } while (0)
; #define PG8_LDA(dst, b, h) do { _Pragma("unroll") for (int m = 0; m < 4; ++m) _Pragma("unroll") for (int k = 0; k < 2; ++k) dst[m][k] = *(const LAS bf16x8*)(lds + PG8_SA(b, h) + aoff + m * 2048 + k * 1024); } while (0)
; #define PG8_LDB(dst, b, h) do { _Pragma("unroll") for (int n = 0; n < 2; ++n) _Pragma("unroll") for (int k = 0; k < 2; ++k) dst[n][k] = *(const LAS bf16x8*)(lds + PG8_SB(b, h) + boff + n * 2048 + k * 1024); } while (0)
; #define PG8_MMA(ai, bj, At, Bt) do { __builtin_amdgcn_s_setprio(1); _Pragma("unroll") for (int m = 0; m < 4; ++m) _Pragma("unroll") for (int n = 0; n < 2; ++n) _Pragma("unroll") for (int k = 0; k < 2; ++k) \
;         acc[ai][bj][m][n] = __builtin_amdgcn_mfma_f32_16x16x32_bf16(Bt[n][k], At[m][k], acc[ai][bj][m][n], 0, 0, 0); __builtin_amdgcn_s_setprio(0); } while (0)
; #define PG8_WAIT_V(n) asm volatile("s_waitcnt vmcnt(" #n ")" ::: "memory")
; #define PG8_WAIT_L(n) asm volatile("s_waitcnt lgkmcnt(" #n ")" ::: "memory")
; #define PG8_BAR __builtin_amdgcn_s_barrier()
; #define PG8_SCHED __builtin_amdgcn_sched_barrier(0)
; template <class Epi, class Sched>
; __device__ __forceinline__ void gemm_phase(LAS unsigned char* lds, const Gemm g, const Sched S, const Epi E, const int tid) {
;     ...
;             PG8_LDB(B0, 0, 0); PG8_LDB(B1, 0, 1); PG8_SCHED; PG8_LDA(At, 0, 0); PG8_STAGE(PG8_SA(1, 1), a1 + hstepA, voffA);
;             PG8_WAIT_V(8); PG8_WAIT_L(0); PG8_BAR; PG8_MMA(0, 0, At, B0); PG8_MMA(0, 1, At, B1); PG8_BAR; PG8_SCHED;
;     ...
;             PG8_WAIT_V(8); PG8_WAIT_L(0); PG8_BAR; PG8_MMA(0, 0, At, B0); PG8_MMA(0, 1, At, B1); PG8_BAR; PG8_SCHED;
;             PG8_LDA(At, 1, 1); PG8_STAGE(PG8_SB(1, 0), b3, voffB); PG8_STAGE(PG8_SB(1, 1), b3 + hstepB, voffB); PG8_STAGE(PG8_SA(1, 0), a3, voffA);
;             PG8_WAIT_V(8); PG8_WAIT_L(0); PG8_BAR; PG8_MMA(1, 0, At, B0); PG8_MMA(1, 1, At, B1); PG8_BAR; PG8_SCHED;
	s_setprio 1
	v_mfma_f32_16x16x32_bf16 v[50:53], v[10:13], v[84:87], v[50:53]
	v_mfma_f32_16x16x32_bf16 v[18:21], v[76:79], v[84:87], v[18:21]
	v_mfma_f32_16x16x32_bf16 v[22:25], v[10:13], v[96:99], v[22:25]
	v_mfma_f32_16x16x32_bf16 v[26:29], v[76:79], v[96:99], v[26:29]
	v_mfma_f32_16x16x32_bf16 v[30:33], v[10:13], v[104:107], v[30:33]
	v_mfma_f32_16x16x32_bf16 v[34:37], v[76:79], v[104:107], v[34:37]
	v_mfma_f32_16x16x32_bf16 v[38:41], v[10:13], v[112:115], v[38:41]
	v_mfma_f32_16x16x32_bf16 v[42:45], v[76:79], v[112:115], v[42:45]
	v_mfma_f32_16x16x32_bf16 v[50:53], v[14:17], v[92:95], v[50:53]
	v_mfma_f32_16x16x32_bf16 v[18:21], v[80:83], v[92:95], v[18:21]
	v_mfma_f32_16x16x32_bf16 v[22:25], v[14:17], v[100:103], v[22:25]
	v_mfma_f32_16x16x32_bf16 v[26:29], v[80:83], v[100:103], v[26:29]
	v_mfma_f32_16x16x32_bf16 v[30:33], v[14:17], v[108:111], v[30:33]
	v_mfma_f32_16x16x32_bf16 v[34:37], v[80:83], v[108:111], v[34:37]
	v_mfma_f32_16x16x32_bf16 v[38:41], v[14:17], v[116:119], v[38:41]
	v_mfma_f32_16x16x32_bf16 v[42:45], v[80:83], v[116:119], v[42:45]
	s_setprio 0
	s_barrier
	s_add_i32 vcc_lo, s45, s47
	s_mov_b64 s[6:7], 0x180
	s_add_i32 s95, vcc_lo, 0x2000
	v_lshl_add_u64 v[120:121], v[120:121], 0, s[6:7]
	s_mov_b32 m0, vcc_lo
	s_add_u32 s10, s42, 0x10180
	ds_read_b128 v[84:87], v71 offset:49152
	ds_read_b128 v[92:95], v71 offset:50176
	ds_read_b128 v[96:99], v71 offset:51200
	ds_read_b128 v[100:103], v71 offset:52224
	ds_read_b128 v[104:107], v71 offset:53248
	ds_read_b128 v[108:111], v71 offset:54272
	ds_read_b128 v[112:115], v71 offset:55296
	ds_read_b128 v[116:119], v71 offset:56320
	global_load_lds_dwordx4 v[120:121], off
	v_lshl_add_u64 v[120:121], v[122:123], 0, s[6:7]
	s_mov_b32 m0, s95
	s_addc_u32 s11, s43, 0
	global_load_lds_dwordx4 v[120:121], off
	v_lshl_add_u64 v[120:121], s[10:11], 0, v[68:69]
	s_mov_b32 m0, s85
	s_nop 0
	global_load_lds_dwordx4 v[120:121], off
	v_lshl_add_u64 v[120:121], s[10:11], 0, v[66:67]
	s_mov_b32 m0, s88
	s_nop 0
	global_load_lds_dwordx4 v[120:121], off
	v_lshl_add_u64 v[120:121], v[124:125], 0, s[6:7]
	s_mov_b32 m0, s83
	s_nop 0
	global_load_lds_dwordx4 v[120:121], off
	v_lshl_add_u64 v[120:121], v[126:127], 0, s[6:7]
	s_mov_b32 m0, s84
	s_nop 0
	global_load_lds_dwordx4 v[120:121], off
	s_waitcnt vmcnt(8)
	s_waitcnt lgkmcnt(0)
	s_barrier
	s_setprio 1
	v_mfma_f32_16x16x32_bf16 v[46:49], v[76:79], v[84:87], v[46:49]
	v_mfma_f32_16x16x32_bf16 v[54:57], v[10:13], v[96:99], v[54:57]
	v_mfma_f32_16x16x32_bf16 v[58:61], v[76:79], v[96:99], v[58:61]
	v_mfma_f32_16x16x32_bf16 v[62:65], v[10:13], v[104:107], v[62:65]
	v_mfma_f32_16x16x32_bf16 v[2:5], v[10:13], v[112:115], v[2:5]
	v_mfma_f32_16x16x32_bf16 v[6:9], v[76:79], v[112:115], v[6:9]
	v_mfma_f32_16x16x32_bf16 v[88:91], v[10:13], v[84:87], v[88:91]
	v_mfma_f32_16x16x32_bf16 v[46:49], v[80:83], v[92:95], v[46:49]
	v_mfma_f32_16x16x32_bf16 v[54:57], v[14:17], v[100:103], v[54:57]
	v_mfma_f32_16x16x32_bf16 v[58:61], v[80:83], v[100:103], v[58:61]
	v_mfma_f32_16x16x32_bf16 v[62:65], v[14:17], v[108:111], v[62:65]
	v_mfma_f32_16x16x32_bf16 v[72:75], v[76:79], v[104:107], v[72:75]
	v_mfma_f32_16x16x32_bf16 v[2:5], v[14:17], v[116:119], v[2:5]
	v_mfma_f32_16x16x32_bf16 v[6:9], v[80:83], v[116:119], v[6:9]
	v_mfma_f32_16x16x32_bf16 v[88:91], v[14:17], v[92:95], v[88:91]
	v_mfma_f32_16x16x32_bf16 v[72:75], v[80:83], v[108:111], v[72:75]
	s_setprio 0
	s_barrier
	ds_read_b128 v[10:13], v130
	ds_read_b128 v[14:17], v130 offset:1024
	ds_read_b128 v[76:79], v130 offset:2048
	ds_read_b128 v[80:83], v130 offset:3072
	s_add_u32 s10, s40, 0x10180
	s_addc_u32 s11, s41, 0
	s_mov_b32 m0, s97
	v_lshl_add_u64 v[120:121], s[10:11], 0, v[68:69]
	ds_read_b128 v[84:87], v71
	ds_read_b128 v[92:95], v71 offset:1024
	ds_read_b128 v[96:99], v71 offset:2048
	ds_read_b128 v[100:103], v71 offset:3072
	ds_read_b128 v[104:107], v71 offset:4096
	ds_read_b128 v[108:111], v71 offset:5120
	ds_read_b128 v[112:115], v71 offset:6144
	ds_read_b128 v[116:119], v71 offset:7168
	global_load_lds_dwordx4 v[120:121], off
	v_lshl_add_u64 v[120:121], s[10:11], 0, v[66:67]
	s_mov_b32 m0, s13
	s_nop 0
	global_load_lds_dwordx4 v[120:121], off
	s_waitcnt vmcnt(8)
	s_waitcnt lgkmcnt(0)
	s_barrier
	s_setprio 1
	v_mfma_f32_16x16x32_bf16 v[38:41], v[10:13], v[112:115], v[38:41]
	v_mfma_f32_16x16x32_bf16 v[50:53], v[10:13], v[84:87], v[50:53]
	v_mfma_f32_16x16x32_bf16 v[18:21], v[76:79], v[84:87], v[18:21]
	v_mfma_f32_16x16x32_bf16 v[22:25], v[10:13], v[96:99], v[22:25]
	v_mfma_f32_16x16x32_bf16 v[26:29], v[76:79], v[96:99], v[26:29]
	v_mfma_f32_16x16x32_bf16 v[30:33], v[10:13], v[104:107], v[30:33]
	v_mfma_f32_16x16x32_bf16 v[34:37], v[76:79], v[104:107], v[34:37]
	v_mfma_f32_16x16x32_bf16 v[84:87], v[14:17], v[116:119], v[38:41]
	v_mfma_f32_16x16x32_bf16 v[38:41], v[76:79], v[112:115], v[42:45]
	v_mfma_f32_16x16x32_bf16 v[50:53], v[14:17], v[92:95], v[50:53]
	v_mfma_f32_16x16x32_bf16 v[18:21], v[80:83], v[92:95], v[18:21]
	v_mfma_f32_16x16x32_bf16 v[22:25], v[14:17], v[100:103], v[22:25]
	v_mfma_f32_16x16x32_bf16 v[26:29], v[80:83], v[100:103], v[26:29]
	v_mfma_f32_16x16x32_bf16 v[30:33], v[14:17], v[108:111], v[30:33]
	v_mfma_f32_16x16x32_bf16 v[34:37], v[80:83], v[108:111], v[34:37]
	v_mfma_f32_16x16x32_bf16 v[42:45], v[80:83], v[116:119], v[38:41]
	s_setprio 0
	s_barrier
; #define PG8_STAGE(bufoff, gbase, voff) do { _Pragma("unroll") for (int _i = 0; _i < 2; ++_i) \
;         __builtin_amdgcn_global_load_lds((const unsigned*)((const char*)(gbase) + (voff)[_i]), (LAS unsigned*)(lds + (bufoff) + ldsw + _i * 8192), 16, 0, 0); } while (0)
; #define PG8_LDA(dst, b, h) do { _Pragma("unroll") for (int m = 0; m < 4; ++m) _Pragma("unroll") for (int k = 0; k < 2; ++k) dst[m][k] = *(const LAS bf16x8*)(lds + PG8_SA(b, h) + aoff + m * 2048 + k * 1024); } while (0)
; #define PG8_LDB(dst, b, h) do { _Pragma("unroll") for (int n = 0; n < 2; ++n) _Pragma("unroll") for (int k = 0; k < 2; ++k) dst[n][k] = *(const LAS bf16x8*)(lds + PG8_SB(b, h) + boff + n * 2048 + k * 1024); } while (0)
; #define PG8_MMA(ai, bj, At, Bt) do { __builtin_amdgcn_s_setprio(1); _Pragma("unroll") for (int m = 0; m < 4; ++m) _Pragma("unroll") for (int n = 0; n < 2; ++n) _Pragma("unroll") for (int k = 0; k < 2; ++k) \
;         acc[ai][bj][m][n] = __builtin_amdgcn_mfma_f32_16x16x32_bf16(Bt[n][k], At[m][k], acc[ai][bj][m][n], 0, 0, 0); __builtin_amdgcn_s_setprio(0); } while (0)
; #define PG8_WAIT_V(n) asm volatile("s_waitcnt vmcnt(" #n ")" ::: "memory")
; #define PG8_WAIT_L(n) asm volatile("s_waitcnt lgkmcnt(" #n ")" ::: "memory")
; #define PG8_BAR __builtin_amdgcn_s_barrier()
; template <class Epi, class Sched>
; __device__ __forceinline__ void gemm_phase(LAS unsigned char* lds, const Gemm g, const Sched S, const Epi E, const int tid) {
;     ...
;             PG8_WAIT_V(8); PG8_WAIT_L(0); PG8_BAR; PG8_MMA(0, 0, At, B0); PG8_MMA(0, 1, At, B1); PG8_BAR; PG8_SCHED;
;             PG8_LDA(At, 0, 1); PG8_STAGE(PG8_SB(0, 0), b2, voffB); PG8_STAGE(PG8_SB(0, 1), b2 + hstepB, voffB); PG8_STAGE(PG8_SA(0, 0), a2, voffA);
;             PG8_WAIT_V(8); PG8_WAIT_L(0); PG8_BAR; PG8_MMA(1, 0, At, B0); PG8_MMA(1, 1, At, B1); PG8_BAR; PG8_SCHED;
;             PG8_LDB(B0, 1, 0); PG8_LDB(B1, 1, 1); PG8_SCHED; PG8_LDA(At, 1, 0); PG8_STAGE(PG8_SA(0, 1), a2 + hstepA, voffA);
;             PG8_WAIT_V(8); PG8_WAIT_L(0); PG8_BAR; PG8_MMA(0, 0, At, B0); PG8_MMA(0, 1, At, B1); PG8_BAR; PG8_SCHED;
;             PG8_LDA(At, 1, 1); PG8_STAGE(PG8_SB(1, 0), b3, voffB); PG8_STAGE(PG8_SB(1, 1), b3 + hstepB, voffB); PG8_STAGE(PG8_SA(1, 0), a3, voffA);
;             PG8_WAIT_V(8); PG8_WAIT_L(0); PG8_BAR; PG8_MMA(1, 0, At, B0); PG8_MMA(1, 1, At, B1); PG8_BAR; PG8_SCHED;
;         }
;         if (wr == 0) PG8_BAR;
	s_mov_b32 m0, s96
	v_lshl_add_u64 v[132:133], s[26:27], 0, v[68:69]
	s_add_u32 s10, s26, 0x10000
	ds_read_b128 v[38:41], v71 offset:16384
	ds_read_b128 v[92:95], v71 offset:17408
	ds_read_b128 v[96:99], v71 offset:18432
	ds_read_b128 v[100:103], v71 offset:19456
	ds_read_b128 v[104:107], v71 offset:20480
	ds_read_b128 v[108:111], v71 offset:21504
	ds_read_b128 v[112:115], v71 offset:22528
	ds_read_b128 v[116:119], v71 offset:23552
	global_load_lds_dwordx4 v[132:133], off
	v_lshl_add_u64 v[134:135], s[26:27], 0, v[66:67]
	s_mov_b32 m0, s94
	s_addc_u32 s11, s27, 0
	global_load_lds_dwordx4 v[134:135], off
	v_lshl_add_u64 v[120:121], s[10:11], 0, v[68:69]
	s_mov_b32 m0, s48
	v_lshl_add_u64 v[136:137], s[28:29], 0, v[68:69]
	global_load_lds_dwordx4 v[120:121], off
	v_lshl_add_u64 v[120:121], s[10:11], 0, v[66:67]
	s_mov_b32 m0, s49
	v_lshl_add_u64 v[138:139], s[28:29], 0, v[66:67]
	global_load_lds_dwordx4 v[120:121], off
	s_mov_b32 m0, s37
	s_nop 0
	global_load_lds_dwordx4 v[136:137], off
	s_mov_b32 m0, s62
	s_nop 0
	global_load_lds_dwordx4 v[138:139], off
	s_waitcnt vmcnt(8)
	s_waitcnt lgkmcnt(0)
	s_barrier
	s_setprio 1
	v_mfma_f32_16x16x32_bf16 v[88:91], v[10:13], v[38:41], v[88:91]
	v_mfma_f32_16x16x32_bf16 v[38:41], v[76:79], v[38:41], v[46:49]
	v_mfma_f32_16x16x32_bf16 v[88:91], v[14:17], v[92:95], v[88:91]
	v_mfma_f32_16x16x32_bf16 v[92:95], v[80:83], v[92:95], v[38:41]
	v_mfma_f32_16x16x32_bf16 v[38:41], v[10:13], v[96:99], v[54:57]
	v_mfma_f32_16x16x32_bf16 v[120:123], v[14:17], v[100:103], v[38:41]
	v_mfma_f32_16x16x32_bf16 v[38:41], v[76:79], v[96:99], v[58:61]
	v_mfma_f32_16x16x32_bf16 v[96:99], v[80:83], v[100:103], v[38:41]
	v_mfma_f32_16x16x32_bf16 v[38:41], v[10:13], v[104:107], v[62:65]
	v_mfma_f32_16x16x32_bf16 v[2:5], v[10:13], v[112:115], v[2:5]
	v_mfma_f32_16x16x32_bf16 v[100:103], v[14:17], v[108:111], v[38:41]
	v_mfma_f32_16x16x32_bf16 v[38:41], v[76:79], v[104:107], v[72:75]
	v_mfma_f32_16x16x32_bf16 v[2:5], v[14:17], v[116:119], v[2:5]
	v_mfma_f32_16x16x32_bf16 v[6:9], v[76:79], v[112:115], v[6:9]
	v_mfma_f32_16x16x32_bf16 v[72:75], v[80:83], v[108:111], v[38:41]
	v_mfma_f32_16x16x32_bf16 v[76:79], v[80:83], v[116:119], v[6:9]
	s_setprio 0
	s_barrier
	s_nop 1
	ds_read_b128 v[6:9], v131
	ds_read_b128 v[80:83], v131 offset:1024
	ds_read_b128 v[104:107], v131 offset:2048
	ds_read_b128 v[108:111], v131 offset:3072
	s_add_u32 s10, s28, 0x10000
	s_addc_u32 s11, s29, 0
	s_mov_b32 m0, s68
	v_lshl_add_u64 v[54:55], s[10:11], 0, v[68:69]
	ds_read_b128 v[10:13], v71 offset:32768
	ds_read_b128 v[14:17], v71 offset:33792
	ds_read_b128 v[38:41], v71 offset:34816
	ds_read_b128 v[46:49], v71 offset:35840
	ds_read_b128 v[112:115], v71 offset:36864
	ds_read_b128 v[116:119], v71 offset:37888
	ds_read_b128 v[124:127], v71 offset:38912
	ds_read_b128 v[128:131], v71 offset:39936
	global_load_lds_dwordx4 v[54:55], off
	v_lshl_add_u64 v[54:55], s[10:11], 0, v[66:67]
	s_mov_b32 m0, s69
	s_nop 0
	global_load_lds_dwordx4 v[54:55], off
	s_waitcnt vmcnt(8)
	s_waitcnt lgkmcnt(0)
	s_barrier
	s_setprio 1
	v_mfma_f32_16x16x32_bf16 v[50:53], v[6:9], v[10:13], v[50:53]
	v_mfma_f32_16x16x32_bf16 v[10:13], v[104:107], v[10:13], v[18:21]
	v_mfma_f32_16x16x32_bf16 v[58:61], v[108:111], v[14:17], v[10:13]
	v_mfma_f32_16x16x32_bf16 v[10:13], v[6:9], v[38:41], v[22:25]
	v_mfma_f32_16x16x32_bf16 v[54:57], v[80:83], v[46:49], v[10:13]
	v_mfma_f32_16x16x32_bf16 v[10:13], v[104:107], v[38:41], v[26:29]
	v_mfma_f32_16x16x32_bf16 v[62:65], v[80:83], v[14:17], v[50:53]
	v_mfma_f32_16x16x32_bf16 v[50:53], v[108:111], v[46:49], v[10:13]
	v_mfma_f32_16x16x32_bf16 v[10:13], v[6:9], v[112:115], v[30:33]
	v_mfma_f32_16x16x32_bf16 v[46:49], v[80:83], v[116:119], v[10:13]
	v_mfma_f32_16x16x32_bf16 v[10:13], v[104:107], v[112:115], v[34:37]
	v_mfma_f32_16x16x32_bf16 v[38:41], v[108:111], v[116:119], v[10:13]
	v_mfma_f32_16x16x32_bf16 v[10:13], v[6:9], v[124:127], v[84:87]
	v_mfma_f32_16x16x32_bf16 v[30:33], v[80:83], v[128:131], v[10:13]
	v_mfma_f32_16x16x32_bf16 v[10:13], v[104:107], v[124:127], v[42:45]
	v_mfma_f32_16x16x32_bf16 v[22:25], v[108:111], v[128:131], v[10:13]
	s_setprio 0
	s_barrier
	s_mov_b32 m0, vcc_lo
	v_lshl_add_u64 v[26:27], v[132:133], 0, s[64:65]
	s_add_u32 s10, s26, 0x10080
	ds_read_b128 v[10:13], v71 offset:49152
	ds_read_b128 v[14:17], v71 offset:50176
	ds_read_b128 v[18:21], v71 offset:51200
	ds_read_b128 v[84:87], v71 offset:52224
	ds_read_b128 v[112:115], v71 offset:53248
	ds_read_b128 v[116:119], v71 offset:54272
	ds_read_b128 v[124:127], v71 offset:55296
	ds_read_b128 v[128:131], v71 offset:56320
	global_load_lds_dwordx4 v[26:27], off
	v_lshl_add_u64 v[26:27], v[134:135], 0, s[64:65]
	s_mov_b32 m0, s95
	s_addc_u32 s11, s27, 0
	global_load_lds_dwordx4 v[26:27], off
	v_lshl_add_u64 v[26:27], s[10:11], 0, v[68:69]
	s_mov_b32 m0, s85
	s_nop 0
	global_load_lds_dwordx4 v[26:27], off
	v_lshl_add_u64 v[26:27], s[10:11], 0, v[66:67]
	s_mov_b32 m0, s88
	s_nop 0
	global_load_lds_dwordx4 v[26:27], off
	v_lshl_add_u64 v[26:27], v[136:137], 0, s[64:65]
	s_mov_b32 m0, s83
	s_nop 0
	global_load_lds_dwordx4 v[26:27], off
	v_lshl_add_u64 v[26:27], v[138:139], 0, s[64:65]
	s_mov_b32 m0, s84
	s_nop 0
	global_load_lds_dwordx4 v[26:27], off
	s_waitcnt vmcnt(8)
	s_waitcnt lgkmcnt(0)
	s_barrier
	s_setprio 1
	v_mfma_f32_16x16x32_bf16 v[26:29], v[6:9], v[10:13], v[88:91]
	v_mfma_f32_16x16x32_bf16 v[10:13], v[104:107], v[10:13], v[92:95]
	v_mfma_f32_16x16x32_bf16 v[34:37], v[108:111], v[14:17], v[10:13]
	v_mfma_f32_16x16x32_bf16 v[10:13], v[6:9], v[18:21], v[120:123]
	v_mfma_f32_16x16x32_bf16 v[42:45], v[80:83], v[14:17], v[26:29]
	v_mfma_f32_16x16x32_bf16 v[26:29], v[80:83], v[84:87], v[10:13]
	v_mfma_f32_16x16x32_bf16 v[10:13], v[104:107], v[18:21], v[96:99]
	v_mfma_f32_16x16x32_bf16 v[18:21], v[108:111], v[84:87], v[10:13]
	v_mfma_f32_16x16x32_bf16 v[10:13], v[6:9], v[112:115], v[100:103]
	v_mfma_f32_16x16x32_bf16 v[2:5], v[6:9], v[124:127], v[2:5]
	v_mfma_f32_16x16x32_bf16 v[14:17], v[80:83], v[116:119], v[10:13]
	v_mfma_f32_16x16x32_bf16 v[10:13], v[104:107], v[112:115], v[72:75]
	v_mfma_f32_16x16x32_bf16 v[6:9], v[80:83], v[128:131], v[2:5]
	v_mfma_f32_16x16x32_bf16 v[2:5], v[104:107], v[124:127], v[76:79]
	v_mfma_f32_16x16x32_bf16 v[10:13], v[108:111], v[116:119], v[10:13]
	v_mfma_f32_16x16x32_bf16 v[2:5], v[108:111], v[128:131], v[2:5]
	s_setprio 0
	s_barrier
	s_andn2_b64 vcc, exec, s[18:19]
	s_cbranch_vccnz .LBB0_312
	s_barrier

; #define PG8_STAGE(bufoff, gbase, voff) do { _Pragma("unroll") for (int _i = 0; _i < 2; ++_i) \
;         __builtin_amdgcn_global_load_lds((const unsigned*)((const char*)(gbase) + (voff)[_i]), (LAS unsigned*)(lds + (bufoff) + ldsw + _i * 8192), 16, 0, 0); } while (0)
; #define PG8_LDA(dst, b, h) do { _Pragma("unroll") for (int m = 0; m < 4; ++m) _Pragma("unroll") for (int k = 0; k < 2; ++k) dst[m][k] = *(const LAS bf16x8*)(lds + PG8_SA(b, h) + aoff + m * 2048 + k * 1024); } while (0)
; #define PG8_LDB(dst, b, h) do { _Pragma("unroll") for (int n = 0; n < 2; ++n) _Pragma("unroll") for (int k = 0; k < 2; ++k) dst[n][k] = *(const LAS bf16x8*)(lds + PG8_SB(b, h) + boff + n * 2048 + k * 1024); } while (0)
; #define PG8_MMA(ai, bj, At, Bt) do { __builtin_amdgcn_s_setprio(1); _Pragma("unroll") for (int m = 0; m < 4; ++m) _Pragma("unroll") for (int n = 0; n < 2; ++n) _Pragma("unroll") for (int k = 0; k < 2; ++k) \
;         acc[ai][bj][m][n] = __builtin_amdgcn_mfma_f32_16x16x32_bf16(Bt[n][k], At[m][k], acc[ai][bj][m][n], 0, 0, 0); __builtin_amdgcn_s_setprio(0); } while (0)
; #define PG8_WAIT_V(n) asm volatile("s_waitcnt vmcnt(" #n ")" ::: "memory")
; #define PG8_WAIT_L(n) asm volatile("s_waitcnt lgkmcnt(" #n ")" ::: "memory")
; #define PG8_BAR __builtin_amdgcn_s_barrier()
; #define PG8_SCHED __builtin_amdgcn_sched_barrier(0)
; template <class Epi, class Sched>
; __device__ __forceinline__ void gemm_phase(LAS unsigned char* lds, const Gemm g, const Sched S, const Epi E, const int tid) {
;     ...
;             PG8_LDB(B0, 0, 0); PG8_LDB(B1, 0, 1); PG8_SCHED; PG8_LDA(At, 0, 0); PG8_STAGE(PG8_SA(1, 1), a1 + hstepA, voffA);
;             PG8_WAIT_V(8); PG8_WAIT_L(0); PG8_BAR; PG8_MMA(0, 0, At, B0); PG8_MMA(0, 1, At, B1); PG8_BAR; PG8_SCHED;
;             PG8_LDA(At, 0, 1); PG8_STAGE(PG8_SB(0, 0), b2, voffB); PG8_STAGE(PG8_SB(0, 1), b2 + hstepB, voffB); PG8_STAGE(PG8_SA(0, 0), a2, voffA);
;             PG8_WAIT_V(8); PG8_WAIT_L(0); PG8_BAR; PG8_MMA(1, 0, At, B0); PG8_MMA(1, 1, At, B1); PG8_BAR; PG8_SCHED;
.LBB0_332:
	s_add_u32 s10, s44, 0xfffc0080
	s_addc_u32 s11, s45, -1
	s_add_i32 vcc_lo, 0, 0x10000
	s_cmp_eq_u32 s97, 12
	s_cselect_b32 s83, s7, s11
	s_cselect_b32 s82, s92, s10
	v_add_u32_e32 v154, vcc_lo, v157
	s_cselect_b32 s47, s93, s96
	s_cselect_b32 s46, s94, s95
	s_add_i32 vcc_hi, 0, 0x14000
	s_waitcnt lgkmcnt(0)
	ds_read_b128 v[130:133], v154
	ds_read_b128 v[134:137], v154 offset:1024
	ds_read_b128 v[150:153], v154 offset:2048
	ds_read_b128 v[160:163], v154 offset:3072
	v_add_u32_e32 v154, vcc_hi, v157
	ds_read_b128 v[164:167], v154
	ds_read_b128 v[180:183], v154 offset:1024
	ds_read_b128 v[184:187], v154 offset:2048
	ds_read_b128 v[188:191], v154 offset:3072
	v_lshl_add_u64 v[154:155], s[44:45], 0, v[148:149]
	s_add_i32 m0, s48, 0xc000
	ds_read_b128 v[192:195], v158
	ds_read_b128 v[196:199], v158 offset:1024
	ds_read_b128 v[200:203], v158 offset:2048
	ds_read_b128 v[204:207], v158 offset:3072
	ds_read_b128 v[208:211], v158 offset:4096
	ds_read_b128 v[212:215], v158 offset:5120
	ds_read_b128 v[216:219], v158 offset:6144
	ds_read_b128 v[220:223], v158 offset:7168
	global_load_lds_dwordx4 v[154:155], off
	v_lshl_add_u64 v[154:155], s[44:45], 0, v[146:147]
	s_add_i32 m0, s48, 0xe000
	s_nop 0
	global_load_lds_dwordx4 v[154:155], off
	s_waitcnt vmcnt(8)
	s_waitcnt lgkmcnt(0)
	s_barrier
	s_setprio 1
	v_mfma_f32_16x16x32_bf16 v[122:125], v[130:133], v[192:195], v[122:125]
	v_mfma_f32_16x16x32_bf16 v[114:117], v[150:153], v[192:195], v[114:117]
	v_mfma_f32_16x16x32_bf16 v[106:109], v[130:133], v[200:203], v[106:109]
	v_mfma_f32_16x16x32_bf16 v[98:101], v[150:153], v[200:203], v[98:101]
	v_mfma_f32_16x16x32_bf16 v[90:93], v[130:133], v[208:211], v[90:93]
	v_mfma_f32_16x16x32_bf16 v[82:85], v[150:153], v[208:211], v[82:85]
	v_mfma_f32_16x16x32_bf16 v[74:77], v[130:133], v[216:219], v[74:77]
	v_mfma_f32_16x16x32_bf16 v[66:69], v[150:153], v[216:219], v[66:69]
	v_mfma_f32_16x16x32_bf16 v[122:125], v[134:137], v[196:199], v[122:125]
	v_mfma_f32_16x16x32_bf16 v[114:117], v[160:163], v[196:199], v[114:117]
	v_mfma_f32_16x16x32_bf16 v[106:109], v[134:137], v[204:207], v[106:109]
	v_mfma_f32_16x16x32_bf16 v[98:101], v[160:163], v[204:207], v[98:101]
	v_mfma_f32_16x16x32_bf16 v[90:93], v[134:137], v[212:215], v[90:93]
	v_mfma_f32_16x16x32_bf16 v[82:85], v[160:163], v[212:215], v[82:85]
	v_mfma_f32_16x16x32_bf16 v[74:77], v[134:137], v[220:223], v[74:77]
	v_mfma_f32_16x16x32_bf16 v[66:69], v[160:163], v[220:223], v[66:69]
	v_mfma_f32_16x16x32_bf16 v[126:129], v[164:167], v[192:195], v[126:129]
	v_mfma_f32_16x16x32_bf16 v[118:121], v[184:187], v[192:195], v[118:121]
	v_mfma_f32_16x16x32_bf16 v[110:113], v[164:167], v[200:203], v[110:113]
	v_mfma_f32_16x16x32_bf16 v[102:105], v[184:187], v[200:203], v[102:105]
	v_mfma_f32_16x16x32_bf16 v[94:97], v[164:167], v[208:211], v[94:97]
	v_mfma_f32_16x16x32_bf16 v[86:89], v[184:187], v[208:211], v[86:89]
	v_mfma_f32_16x16x32_bf16 v[78:81], v[164:167], v[216:219], v[78:81]
	v_mfma_f32_16x16x32_bf16 v[70:73], v[184:187], v[216:219], v[70:73]
	v_mfma_f32_16x16x32_bf16 v[126:129], v[180:183], v[196:199], v[126:129]
	v_mfma_f32_16x16x32_bf16 v[118:121], v[188:191], v[196:199], v[118:121]
	v_mfma_f32_16x16x32_bf16 v[110:113], v[180:183], v[204:207], v[110:113]
	v_mfma_f32_16x16x32_bf16 v[102:105], v[188:191], v[204:207], v[102:105]
	v_mfma_f32_16x16x32_bf16 v[94:97], v[180:183], v[212:215], v[94:97]
	v_mfma_f32_16x16x32_bf16 v[86:89], v[188:191], v[212:215], v[86:89]
	v_mfma_f32_16x16x32_bf16 v[78:81], v[180:183], v[220:223], v[78:81]
	v_mfma_f32_16x16x32_bf16 v[70:73], v[188:191], v[220:223], v[70:73]
	s_setprio 0
	s_barrier
	s_add_i32 s10, vcc_lo, s37
	v_lshl_add_u64 v[154:155], s[46:47], 0, v[140:141]
	s_mov_b32 m0, s10
	ds_read_b128 v[192:195], v158 offset:16384
	ds_read_b128 v[196:199], v158 offset:17408
	ds_read_b128 v[200:203], v158 offset:18432
	ds_read_b128 v[204:207], v158 offset:19456
	ds_read_b128 v[208:211], v158 offset:20480
	ds_read_b128 v[212:215], v158 offset:21504
	ds_read_b128 v[216:219], v158 offset:22528
	ds_read_b128 v[220:223], v158 offset:23552
	global_load_lds_dwordx4 v[154:155], off
	s_add_i32 m0, s10, 0x2000
	s_add_u32 s10, s46, 0x40000
	v_lshl_add_u64 v[224:225], s[46:47], 0, v[144:145]
	s_addc_u32 s11, s47, 0
	s_add_i32 vcc_lo, vcc_hi, s37
	global_load_lds_dwordx4 v[224:225], off
	v_lshl_add_u64 v[226:227], s[10:11], 0, v[140:141]
	s_mov_b32 m0, vcc_lo
	v_lshl_add_u64 v[228:229], s[82:83], 0, v[142:143]
	global_load_lds_dwordx4 v[226:227], off
	v_lshl_add_u64 v[226:227], s[10:11], 0, v[144:145]
	s_add_i32 m0, vcc_lo, 0x2000
	s_nop 0
	global_load_lds_dwordx4 v[226:227], off
	v_lshl_add_u64 v[226:227], s[82:83], 0, v[138:139]
	s_mov_b32 m0, s48
	s_nop 0
	global_load_lds_dwordx4 v[226:227], off
	s_mov_b32 m0, s49
	s_nop 0
	global_load_lds_dwordx4 v[228:229], off
	s_waitcnt vmcnt(8)
	s_waitcnt lgkmcnt(0)
	s_barrier
; #define PG8_STAGE(bufoff, gbase, voff) do { _Pragma("unroll") for (int _i = 0; _i < 2; ++_i) \
;         __builtin_amdgcn_global_load_lds((const unsigned*)((const char*)(gbase) + (voff)[_i]), (LAS unsigned*)(lds + (bufoff) + ldsw + _i * 8192), 16, 0, 0); } while (0)
; #define PG8_LDA(dst, b, h) do { _Pragma("unroll") for (int m = 0; m < 4; ++m) _Pragma("unroll") for (int k = 0; k < 2; ++k) dst[m][k] = *(const LAS bf16x8*)(lds + PG8_SA(b, h) + aoff + m * 2048 + k * 1024); } while (0)
; #define PG8_LDB(dst, b, h) do { _Pragma("unroll") for (int n = 0; n < 2; ++n) _Pragma("unroll") for (int k = 0; k < 2; ++k) dst[n][k] = *(const LAS bf16x8*)(lds + PG8_SB(b, h) + boff + n * 2048 + k * 1024); } while (0)
; #define PG8_MMA(ai, bj, At, Bt) do { __builtin_amdgcn_s_setprio(1); _Pragma("unroll") for (int m = 0; m < 4; ++m) _Pragma("unroll") for (int n = 0; n < 2; ++n) _Pragma("unroll") for (int k = 0; k < 2; ++k) \
;         acc[ai][bj][m][n] = __builtin_amdgcn_mfma_f32_16x16x32_bf16(Bt[n][k], At[m][k], acc[ai][bj][m][n], 0, 0, 0); __builtin_amdgcn_s_setprio(0); } while (0)
; #define PG8_WAIT_V(n) asm volatile("s_waitcnt vmcnt(" #n ")" ::: "memory")
; #define PG8_WAIT_L(n) asm volatile("s_waitcnt lgkmcnt(" #n ")" ::: "memory")
; #define PG8_BAR __builtin_amdgcn_s_barrier()
; #define PG8_SCHED __builtin_amdgcn_sched_barrier(0)
; template <class Epi, class Sched>
; __device__ __forceinline__ void gemm_phase(LAS unsigned char* lds, const Gemm g, const Sched S, const Epi E, const int tid) {
;     ...
;             PG8_WAIT_V(8); PG8_WAIT_L(0); PG8_BAR; PG8_MMA(1, 0, At, B0); PG8_MMA(1, 1, At, B1); PG8_BAR; PG8_SCHED;
;             PG8_LDB(B0, 1, 0); PG8_LDB(B1, 1, 1); PG8_SCHED; PG8_LDA(At, 1, 0); PG8_STAGE(PG8_SA(0, 1), a2 + hstepA, voffA);
;             PG8_WAIT_V(8); PG8_WAIT_L(0); PG8_BAR; PG8_MMA(0, 0, At, B0); PG8_MMA(0, 1, At, B1); PG8_BAR; PG8_SCHED;
	s_setprio 1
	v_mfma_f32_16x16x32_bf16 v[58:61], v[130:133], v[192:195], v[58:61]
	v_mfma_f32_16x16x32_bf16 v[50:53], v[150:153], v[192:195], v[50:53]
	v_mfma_f32_16x16x32_bf16 v[42:45], v[130:133], v[200:203], v[42:45]
	v_mfma_f32_16x16x32_bf16 v[34:37], v[150:153], v[200:203], v[34:37]
	v_mfma_f32_16x16x32_bf16 v[26:29], v[130:133], v[208:211], v[26:29]
	v_mfma_f32_16x16x32_bf16 v[18:21], v[150:153], v[208:211], v[18:21]
	v_mfma_f32_16x16x32_bf16 v[10:13], v[130:133], v[216:219], v[10:13]
	v_mfma_f32_16x16x32_bf16 v[6:9], v[150:153], v[216:219], v[6:9]
	v_mfma_f32_16x16x32_bf16 v[58:61], v[134:137], v[196:199], v[58:61]
	v_mfma_f32_16x16x32_bf16 v[50:53], v[160:163], v[196:199], v[50:53]
	v_mfma_f32_16x16x32_bf16 v[42:45], v[134:137], v[204:207], v[42:45]
	v_mfma_f32_16x16x32_bf16 v[34:37], v[160:163], v[204:207], v[34:37]
	v_mfma_f32_16x16x32_bf16 v[26:29], v[134:137], v[212:215], v[26:29]
	v_mfma_f32_16x16x32_bf16 v[18:21], v[160:163], v[212:215], v[18:21]
	v_mfma_f32_16x16x32_bf16 v[10:13], v[134:137], v[220:223], v[10:13]
	v_mfma_f32_16x16x32_bf16 v[6:9], v[160:163], v[220:223], v[6:9]
	v_mfma_f32_16x16x32_bf16 v[62:65], v[164:167], v[192:195], v[62:65]
	v_mfma_f32_16x16x32_bf16 v[54:57], v[184:187], v[192:195], v[54:57]
	v_mfma_f32_16x16x32_bf16 v[46:49], v[164:167], v[200:203], v[46:49]
	v_mfma_f32_16x16x32_bf16 v[38:41], v[184:187], v[200:203], v[38:41]
	v_mfma_f32_16x16x32_bf16 v[30:33], v[164:167], v[208:211], v[30:33]
	v_mfma_f32_16x16x32_bf16 v[22:25], v[184:187], v[208:211], v[22:25]
	v_mfma_f32_16x16x32_bf16 v[14:17], v[164:167], v[216:219], v[14:17]
	v_mfma_f32_16x16x32_bf16 v[2:5], v[184:187], v[216:219], v[2:5]
	v_mfma_f32_16x16x32_bf16 v[62:65], v[180:183], v[196:199], v[62:65]
	v_mfma_f32_16x16x32_bf16 v[54:57], v[188:191], v[196:199], v[54:57]
	v_mfma_f32_16x16x32_bf16 v[46:49], v[180:183], v[204:207], v[46:49]
	v_mfma_f32_16x16x32_bf16 v[38:41], v[188:191], v[204:207], v[38:41]
	v_mfma_f32_16x16x32_bf16 v[30:33], v[180:183], v[212:215], v[30:33]
	v_mfma_f32_16x16x32_bf16 v[22:25], v[188:191], v[212:215], v[22:25]
	v_mfma_f32_16x16x32_bf16 v[14:17], v[180:183], v[220:223], v[14:17]
	v_mfma_f32_16x16x32_bf16 v[2:5], v[188:191], v[220:223], v[2:5]
	s_setprio 0
	s_barrier
	s_add_i32 vcc_lo, 0, 0x18000
	v_add_u32_e32 v159, vcc_lo, v157
	s_add_i32 vcc_hi, 0, 0x1c000
	ds_read_b128 v[130:133], v159
	ds_read_b128 v[134:137], v159 offset:1024
	ds_read_b128 v[150:153], v159 offset:2048
	ds_read_b128 v[160:163], v159 offset:3072
	v_add_u32_e32 v159, vcc_hi, v157
	ds_read_b128 v[164:167], v159
	ds_read_b128 v[180:183], v159 offset:1024
	ds_read_b128 v[184:187], v159 offset:2048
	ds_read_b128 v[188:191], v159 offset:3072
	s_add_u32 s10, s82, 0x40000
	s_addc_u32 s11, s83, 0
	s_mov_b32 m0, s62
	v_lshl_add_u64 v[230:231], s[10:11], 0, v[138:139]
	ds_read_b128 v[192:195], v158 offset:32768
	ds_read_b128 v[196:199], v158 offset:33792
	ds_read_b128 v[200:203], v158 offset:34816
	ds_read_b128 v[204:207], v158 offset:35840
	ds_read_b128 v[208:211], v158 offset:36864
	ds_read_b128 v[212:215], v158 offset:37888
	ds_read_b128 v[216:219], v158 offset:38912
	ds_read_b128 v[220:223], v158 offset:39936
	global_load_lds_dwordx4 v[230:231], off
	v_lshl_add_u64 v[230:231], s[10:11], 0, v[142:143]
	s_mov_b32 m0, s68
	s_nop 0
	global_load_lds_dwordx4 v[230:231], off
	s_waitcnt vmcnt(8)
	s_waitcnt lgkmcnt(0)
	s_barrier
	s_setprio 1
	v_mfma_f32_16x16x32_bf16 v[122:125], v[130:133], v[192:195], v[122:125]
	v_mfma_f32_16x16x32_bf16 v[114:117], v[150:153], v[192:195], v[114:117]
	v_mfma_f32_16x16x32_bf16 v[106:109], v[130:133], v[200:203], v[106:109]
	v_mfma_f32_16x16x32_bf16 v[98:101], v[150:153], v[200:203], v[98:101]
	v_mfma_f32_16x16x32_bf16 v[90:93], v[130:133], v[208:211], v[90:93]
	v_mfma_f32_16x16x32_bf16 v[82:85], v[150:153], v[208:211], v[82:85]
	v_mfma_f32_16x16x32_bf16 v[74:77], v[130:133], v[216:219], v[74:77]
	v_mfma_f32_16x16x32_bf16 v[66:69], v[150:153], v[216:219], v[66:69]
	v_mfma_f32_16x16x32_bf16 v[122:125], v[134:137], v[196:199], v[122:125]
	v_mfma_f32_16x16x32_bf16 v[114:117], v[160:163], v[196:199], v[114:117]
	v_mfma_f32_16x16x32_bf16 v[106:109], v[134:137], v[204:207], v[106:109]
	v_mfma_f32_16x16x32_bf16 v[98:101], v[160:163], v[204:207], v[98:101]
	v_mfma_f32_16x16x32_bf16 v[90:93], v[134:137], v[212:215], v[90:93]
	v_mfma_f32_16x16x32_bf16 v[82:85], v[160:163], v[212:215], v[82:85]
	v_mfma_f32_16x16x32_bf16 v[74:77], v[134:137], v[220:223], v[74:77]
	v_mfma_f32_16x16x32_bf16 v[66:69], v[160:163], v[220:223], v[66:69]
	v_mfma_f32_16x16x32_bf16 v[126:129], v[164:167], v[192:195], v[126:129]
	v_mfma_f32_16x16x32_bf16 v[118:121], v[184:187], v[192:195], v[118:121]
	v_mfma_f32_16x16x32_bf16 v[110:113], v[164:167], v[200:203], v[110:113]
	v_mfma_f32_16x16x32_bf16 v[102:105], v[184:187], v[200:203], v[102:105]
	v_mfma_f32_16x16x32_bf16 v[94:97], v[164:167], v[208:211], v[94:97]
	v_mfma_f32_16x16x32_bf16 v[86:89], v[184:187], v[208:211], v[86:89]
	v_mfma_f32_16x16x32_bf16 v[78:81], v[164:167], v[216:219], v[78:81]
	v_mfma_f32_16x16x32_bf16 v[70:73], v[184:187], v[216:219], v[70:73]
	v_mfma_f32_16x16x32_bf16 v[126:129], v[180:183], v[196:199], v[126:129]
	v_mfma_f32_16x16x32_bf16 v[118:121], v[188:191], v[196:199], v[118:121]
	v_mfma_f32_16x16x32_bf16 v[110:113], v[180:183], v[204:207], v[110:113]
	v_mfma_f32_16x16x32_bf16 v[102:105], v[188:191], v[204:207], v[102:105]
	v_mfma_f32_16x16x32_bf16 v[94:97], v[180:183], v[212:215], v[94:97]
	v_mfma_f32_16x16x32_bf16 v[86:89], v[188:191], v[212:215], v[86:89]
	v_mfma_f32_16x16x32_bf16 v[78:81], v[180:183], v[220:223], v[78:81]
	v_mfma_f32_16x16x32_bf16 v[70:73], v[188:191], v[220:223], v[70:73]
	s_setprio 0
	s_barrier
; #define PG8_STAGE(bufoff, gbase, voff) do { _Pragma("unroll") for (int _i = 0; _i < 2; ++_i) \
;         __builtin_amdgcn_global_load_lds((const unsigned*)((const char*)(gbase) + (voff)[_i]), (LAS unsigned*)(lds + (bufoff) + ldsw + _i * 8192), 16, 0, 0); } while (0)
; #define PG8_LDA(dst, b, h) do { _Pragma("unroll") for (int m = 0; m < 4; ++m) _Pragma("unroll") for (int k = 0; k < 2; ++k) dst[m][k] = *(const LAS bf16x8*)(lds + PG8_SA(b, h) + aoff + m * 2048 + k * 1024); } while (0)
; #define PG8_MMA(ai, bj, At, Bt) do { __builtin_amdgcn_s_setprio(1); _Pragma("unroll") for (int m = 0; m < 4; ++m) _Pragma("unroll") for (int n = 0; n < 2; ++n) _Pragma("unroll") for (int k = 0; k < 2; ++k) \
;         acc[ai][bj][m][n] = __builtin_amdgcn_mfma_f32_16x16x32_bf16(Bt[n][k], At[m][k], acc[ai][bj][m][n], 0, 0, 0); __builtin_amdgcn_s_setprio(0); } while (0)
; #define PG8_WAIT_V(n) asm volatile("s_waitcnt vmcnt(" #n ")" ::: "memory")
; #define PG8_WAIT_L(n) asm volatile("s_waitcnt lgkmcnt(" #n ")" ::: "memory")
; #define PG8_BAR __builtin_amdgcn_s_barrier()
; #define PG8_SCHED __builtin_amdgcn_sched_barrier(0)
; template <class Epi, class Sched>
; __device__ __forceinline__ void gemm_phase(LAS unsigned char* lds, const Gemm g, const Sched S, const Epi E, const int tid) {
;     ...
;             PG8_LDA(At, 1, 1); PG8_STAGE(PG8_SB(1, 0), b3, voffB); PG8_STAGE(PG8_SB(1, 1), b3 + hstepB, voffB); PG8_STAGE(PG8_SA(1, 0), a3, voffA);
;             PG8_WAIT_V(8); PG8_WAIT_L(0); PG8_BAR; PG8_MMA(1, 0, At, B0); PG8_MMA(1, 1, At, B1); PG8_BAR; PG8_SCHED;
;         }
	s_add_i32 s10, vcc_lo, s37
	v_lshl_add_u64 v[154:155], v[154:155], 0, s[64:65]
	s_mov_b32 m0, s10
	ds_read_b128 v[192:195], v158 offset:49152
	ds_read_b128 v[196:199], v158 offset:50176
	ds_read_b128 v[200:203], v158 offset:51200
	ds_read_b128 v[204:207], v158 offset:52224
	ds_read_b128 v[208:211], v158 offset:53248
	ds_read_b128 v[212:215], v158 offset:54272
	ds_read_b128 v[216:219], v158 offset:55296
	ds_read_b128 v[220:223], v158 offset:56320
	global_load_lds_dwordx4 v[154:155], off
	s_add_i32 m0, s10, 0x2000
	s_add_u32 s10, s46, 0x40080
	v_lshl_add_u64 v[154:155], v[224:225], 0, s[64:65]
	s_addc_u32 s11, s47, 0
	s_add_i32 s46, vcc_hi, s37
	global_load_lds_dwordx4 v[154:155], off
	v_lshl_add_u64 v[154:155], s[10:11], 0, v[140:141]
	s_mov_b32 m0, s46
	s_nop 0
	global_load_lds_dwordx4 v[154:155], off
	v_lshl_add_u64 v[154:155], s[10:11], 0, v[144:145]
	s_add_i32 m0, s46, 0x2000
	s_nop 0
	global_load_lds_dwordx4 v[154:155], off
	v_lshl_add_u64 v[154:155], v[226:227], 0, s[64:65]
	s_mov_b32 m0, s88
	s_nop 0
	global_load_lds_dwordx4 v[154:155], off
	v_lshl_add_u64 v[154:155], v[228:229], 0, s[64:65]
	s_mov_b32 m0, s89
	s_nop 0
	global_load_lds_dwordx4 v[154:155], off
	s_waitcnt vmcnt(8)
	s_waitcnt lgkmcnt(0)
	s_barrier
	s_setprio 1
	v_mfma_f32_16x16x32_bf16 v[58:61], v[130:133], v[192:195], v[58:61]
	v_mfma_f32_16x16x32_bf16 v[50:53], v[150:153], v[192:195], v[50:53]
	v_mfma_f32_16x16x32_bf16 v[42:45], v[130:133], v[200:203], v[42:45]
	v_mfma_f32_16x16x32_bf16 v[34:37], v[150:153], v[200:203], v[34:37]
	v_mfma_f32_16x16x32_bf16 v[26:29], v[130:133], v[208:211], v[26:29]
	v_mfma_f32_16x16x32_bf16 v[18:21], v[150:153], v[208:211], v[18:21]
	v_mfma_f32_16x16x32_bf16 v[10:13], v[130:133], v[216:219], v[10:13]
	v_mfma_f32_16x16x32_bf16 v[6:9], v[150:153], v[216:219], v[6:9]
	v_mfma_f32_16x16x32_bf16 v[58:61], v[134:137], v[196:199], v[58:61]
	v_mfma_f32_16x16x32_bf16 v[50:53], v[160:163], v[196:199], v[50:53]
	v_mfma_f32_16x16x32_bf16 v[42:45], v[134:137], v[204:207], v[42:45]
	v_mfma_f32_16x16x32_bf16 v[34:37], v[160:163], v[204:207], v[34:37]
	v_mfma_f32_16x16x32_bf16 v[26:29], v[134:137], v[212:215], v[26:29]
	v_mfma_f32_16x16x32_bf16 v[18:21], v[160:163], v[212:215], v[18:21]
	v_mfma_f32_16x16x32_bf16 v[10:13], v[134:137], v[220:223], v[10:13]
	v_mfma_f32_16x16x32_bf16 v[6:9], v[160:163], v[220:223], v[6:9]
	v_mfma_f32_16x16x32_bf16 v[62:65], v[164:167], v[192:195], v[62:65]
	v_mfma_f32_16x16x32_bf16 v[54:57], v[184:187], v[192:195], v[54:57]
	v_mfma_f32_16x16x32_bf16 v[46:49], v[164:167], v[200:203], v[46:49]
	v_mfma_f32_16x16x32_bf16 v[38:41], v[184:187], v[200:203], v[38:41]
	v_mfma_f32_16x16x32_bf16 v[30:33], v[164:167], v[208:211], v[30:33]
	v_mfma_f32_16x16x32_bf16 v[22:25], v[184:187], v[208:211], v[22:25]
	v_mfma_f32_16x16x32_bf16 v[14:17], v[164:167], v[216:219], v[14:17]
	v_mfma_f32_16x16x32_bf16 v[2:5], v[184:187], v[216:219], v[2:5]
	v_mfma_f32_16x16x32_bf16 v[62:65], v[180:183], v[196:199], v[62:65]
	v_mfma_f32_16x16x32_bf16 v[54:57], v[188:191], v[196:199], v[54:57]
	v_mfma_f32_16x16x32_bf16 v[46:49], v[180:183], v[204:207], v[46:49]
	v_mfma_f32_16x16x32_bf16 v[38:41], v[188:191], v[204:207], v[38:41]
	v_mfma_f32_16x16x32_bf16 v[30:33], v[180:183], v[212:215], v[30:33]
	v_mfma_f32_16x16x32_bf16 v[22:25], v[188:191], v[212:215], v[22:25]
	v_mfma_f32_16x16x32_bf16 v[14:17], v[180:183], v[220:223], v[14:17]
	v_mfma_f32_16x16x32_bf16 v[2:5], v[188:191], v[220:223], v[2:5]
	s_setprio 0
	s_barrier
	s_add_i32 s97, s97, 2
	s_add_u32 s95, s95, 0x100
	s_addc_u32 s96, s96, 0
	s_add_u32 s44, s44, 0x100
	s_addc_u32 s45, s45, 0
	s_cmp_gt_u32 s97, 13
	s_cbranch_scc0 .LBB0_332
	s_and_b64 vcc, exec, s[14:15]
	s_cbranch_vccz .LBB0_335
	s_barrier

; #define PG8_STAGE(bufoff, gbase, voff) do { _Pragma("unroll") for (int _i = 0; _i < 2; ++_i) \
;         __builtin_amdgcn_global_load_lds((const unsigned*)((const char*)(gbase) + (voff)[_i]), (LAS unsigned*)(lds + (bufoff) + ldsw + _i * 8192), 16, 0, 0); } while (0)
; #define PG8_LDA(dst, b, h) do { _Pragma("unroll") for (int m = 0; m < 4; ++m) _Pragma("unroll") for (int k = 0; k < 2; ++k) dst[m][k] = *(const LAS bf16x8*)(lds + PG8_SA(b, h) + aoff + m * 2048 + k * 1024); } while (0)
; #define PG8_LDB(dst, b, h) do { _Pragma("unroll") for (int n = 0; n < 2; ++n) _Pragma("unroll") for (int k = 0; k < 2; ++k) dst[n][k] = *(const LAS bf16x8*)(lds + PG8_SB(b, h) + boff + n * 2048 + k * 1024); } while (0)
; #define PG8_MMA(ai, bj, At, Bt) do { __builtin_amdgcn_s_setprio(1); _Pragma("unroll") for (int m = 0; m < 4; ++m) _Pragma("unroll") for (int n = 0; n < 2; ++n) _Pragma("unroll") for (int k = 0; k < 2; ++k) \
;         acc[ai][bj][m][n] = __builtin_amdgcn_mfma_f32_16x16x32_bf16(Bt[n][k], At[m][k], acc[ai][bj][m][n], 0, 0, 0); __builtin_amdgcn_s_setprio(0); } while (0)
; #define PG8_WAIT_V(n) asm volatile("s_waitcnt vmcnt(" #n ")" ::: "memory")
; #define PG8_WAIT_L(n) asm volatile("s_waitcnt lgkmcnt(" #n ")" ::: "memory")
; #define PG8_BAR __builtin_amdgcn_s_barrier()
; #define PG8_SCHED __builtin_amdgcn_sched_barrier(0)
; template <class Epi, class Sched>
; __device__ __forceinline__ void gemm_phase(LAS unsigned char* lds, const Gemm g, const Sched S, const Epi E, const int tid) {
;     ...
;             PG8_LDB(B0, 0, 0); PG8_LDB(B1, 0, 1); PG8_SCHED; PG8_LDA(At, 0, 0); PG8_STAGE(PG8_SA(1, 1), a1 + hstepA, voffA);
;             PG8_WAIT_V(8); PG8_WAIT_L(0); PG8_BAR; PG8_MMA(0, 0, At, B0); PG8_MMA(0, 1, At, B1); PG8_BAR; PG8_SCHED;
;             PG8_LDA(At, 0, 1); PG8_STAGE(PG8_SB(0, 0), b2, voffB); PG8_STAGE(PG8_SB(0, 1), b2 + hstepB, voffB); PG8_STAGE(PG8_SA(0, 0), a2, voffA);
;             PG8_WAIT_V(8); PG8_WAIT_L(0); PG8_BAR; PG8_MMA(1, 0, At, B0); PG8_MMA(1, 1, At, B1); PG8_BAR; PG8_SCHED;
.LBB0_471:
	s_add_u32 s12, s10, 0xfffc0080
	s_addc_u32 s13, s11, -1
	s_add_i32 s83, 0, 0x10000
	s_cmp_eq_u32 s82, 12
	s_cselect_b32 s15, s9, s13
	s_cselect_b32 s14, s45, s12
	s_cselect_b32 s13, s43, s62
	s_cselect_b32 s12, s48, s49
	s_add_i32 vcc_lo, 0, 0x14000
	v_add_u32_e32 v154, s83, v165
	v_add_u32_e32 v162, vcc_lo, v165
	ds_read_b128 v[50:53], v154
	ds_read_b128 v[102:105], v154 offset:1024
	ds_read_b128 v[150:153], v154 offset:2048
	ds_read_b128 v[154:157], v154 offset:3072
	ds_read_b128 v[158:161], v162
	ds_read_b128 v[180:183], v162 offset:1024
	ds_read_b128 v[184:187], v162 offset:2048
	ds_read_b128 v[188:191], v162 offset:3072
	v_lshl_add_u64 v[162:163], s[10:11], 0, v[148:149]
	s_add_i32 m0, s41, 0xc000
	ds_read_b128 v[192:195], v166
	ds_read_b128 v[196:199], v166 offset:1024
	ds_read_b128 v[200:203], v166 offset:2048
	ds_read_b128 v[204:207], v166 offset:3072
	ds_read_b128 v[208:211], v166 offset:4096
	ds_read_b128 v[212:215], v166 offset:5120
	ds_read_b128 v[216:219], v166 offset:6144
	ds_read_b128 v[220:223], v166 offset:7168
	global_load_lds_dwordx4 v[162:163], off
	v_lshl_add_u64 v[162:163], s[10:11], 0, v[146:147]
	s_add_i32 m0, s41, 0xe000
	s_nop 0
	global_load_lds_dwordx4 v[162:163], off
	s_waitcnt vmcnt(8)
	s_waitcnt lgkmcnt(0)
	s_barrier
	s_setprio 1
	v_mfma_f32_16x16x32_bf16 v[130:133], v[50:53], v[192:195], v[130:133]
	v_mfma_f32_16x16x32_bf16 v[126:129], v[150:153], v[192:195], v[126:129]
	v_mfma_f32_16x16x32_bf16 v[114:117], v[50:53], v[200:203], v[114:117]
	v_mfma_f32_16x16x32_bf16 v[110:113], v[150:153], v[200:203], v[110:113]
	v_mfma_f32_16x16x32_bf16 v[94:97], v[50:53], v[208:211], v[94:97]
	v_mfma_f32_16x16x32_bf16 v[90:93], v[150:153], v[208:211], v[90:93]
	v_mfma_f32_16x16x32_bf16 v[78:81], v[50:53], v[216:219], v[78:81]
	v_mfma_f32_16x16x32_bf16 v[74:77], v[150:153], v[216:219], v[74:77]
	v_mfma_f32_16x16x32_bf16 v[130:133], v[102:105], v[196:199], v[130:133]
	v_mfma_f32_16x16x32_bf16 v[126:129], v[154:157], v[196:199], v[126:129]
	v_mfma_f32_16x16x32_bf16 v[114:117], v[102:105], v[204:207], v[114:117]
	v_mfma_f32_16x16x32_bf16 v[110:113], v[154:157], v[204:207], v[110:113]
	v_mfma_f32_16x16x32_bf16 v[94:97], v[102:105], v[212:215], v[94:97]
	v_mfma_f32_16x16x32_bf16 v[90:93], v[154:157], v[212:215], v[90:93]
	v_mfma_f32_16x16x32_bf16 v[78:81], v[102:105], v[220:223], v[78:81]
	v_mfma_f32_16x16x32_bf16 v[74:77], v[154:157], v[220:223], v[74:77]
	v_mfma_f32_16x16x32_bf16 v[134:137], v[158:161], v[192:195], v[134:137]
	v_mfma_f32_16x16x32_bf16 v[122:125], v[184:187], v[192:195], v[122:125]
	v_mfma_f32_16x16x32_bf16 v[118:121], v[158:161], v[200:203], v[118:121]
	v_mfma_f32_16x16x32_bf16 v[106:109], v[184:187], v[200:203], v[106:109]
	v_mfma_f32_16x16x32_bf16 v[98:101], v[158:161], v[208:211], v[98:101]
	v_mfma_f32_16x16x32_bf16 v[86:89], v[184:187], v[208:211], v[86:89]
	v_mfma_f32_16x16x32_bf16 v[82:85], v[158:161], v[216:219], v[82:85]
	v_mfma_f32_16x16x32_bf16 v[70:73], v[184:187], v[216:219], v[70:73]
	v_mfma_f32_16x16x32_bf16 v[134:137], v[180:183], v[196:199], v[134:137]
	v_mfma_f32_16x16x32_bf16 v[122:125], v[188:191], v[196:199], v[122:125]
	v_mfma_f32_16x16x32_bf16 v[118:121], v[180:183], v[204:207], v[118:121]
	v_mfma_f32_16x16x32_bf16 v[106:109], v[188:191], v[204:207], v[106:109]
	v_mfma_f32_16x16x32_bf16 v[98:101], v[180:183], v[212:215], v[98:101]
	v_mfma_f32_16x16x32_bf16 v[86:89], v[188:191], v[212:215], v[86:89]
	v_mfma_f32_16x16x32_bf16 v[82:85], v[180:183], v[220:223], v[82:85]
	v_mfma_f32_16x16x32_bf16 v[70:73], v[188:191], v[220:223], v[70:73]
	s_setprio 0
	s_barrier
	s_add_i32 s83, s83, s37
	v_lshl_add_u64 v[162:163], s[12:13], 0, v[140:141]
	s_mov_b32 m0, s83
	ds_read_b128 v[192:195], v166 offset:16384
	ds_read_b128 v[196:199], v166 offset:17408
	ds_read_b128 v[200:203], v166 offset:18432
	ds_read_b128 v[204:207], v166 offset:19456
	ds_read_b128 v[208:211], v166 offset:20480
	ds_read_b128 v[212:215], v166 offset:21504
	ds_read_b128 v[216:219], v166 offset:22528
	ds_read_b128 v[220:223], v166 offset:23552
	global_load_lds_dwordx4 v[162:163], off
	s_add_i32 m0, s83, 0x2000
	s_add_u32 s84, s12, 0x40000
	v_lshl_add_u64 v[224:225], s[12:13], 0, v[144:145]
	s_addc_u32 s85, s13, 0
	s_add_i32 s83, vcc_lo, s37
	global_load_lds_dwordx4 v[224:225], off
	v_lshl_add_u64 v[226:227], s[84:85], 0, v[140:141]
	s_mov_b32 m0, s83
	v_lshl_add_u64 v[228:229], s[14:15], 0, v[142:143]
	global_load_lds_dwordx4 v[226:227], off
	v_lshl_add_u64 v[226:227], s[84:85], 0, v[144:145]
	s_add_i32 m0, s83, 0x2000
	s_nop 0
	global_load_lds_dwordx4 v[226:227], off
	v_lshl_add_u64 v[226:227], s[14:15], 0, v[138:139]
	s_mov_b32 m0, s41
	s_nop 0
	global_load_lds_dwordx4 v[226:227], off
	s_mov_b32 m0, s90
	s_nop 0
	global_load_lds_dwordx4 v[228:229], off
	s_waitcnt vmcnt(8)
	s_waitcnt lgkmcnt(0)
	s_barrier
; #define PG8_STAGE(bufoff, gbase, voff) do { _Pragma("unroll") for (int _i = 0; _i < 2; ++_i) \
;         __builtin_amdgcn_global_load_lds((const unsigned*)((const char*)(gbase) + (voff)[_i]), (LAS unsigned*)(lds + (bufoff) + ldsw + _i * 8192), 16, 0, 0); } while (0)
; #define PG8_LDA(dst, b, h) do { _Pragma("unroll") for (int m = 0; m < 4; ++m) _Pragma("unroll") for (int k = 0; k < 2; ++k) dst[m][k] = *(const LAS bf16x8*)(lds + PG8_SA(b, h) + aoff + m * 2048 + k * 1024); } while (0)
; #define PG8_LDB(dst, b, h) do { _Pragma("unroll") for (int n = 0; n < 2; ++n) _Pragma("unroll") for (int k = 0; k < 2; ++k) dst[n][k] = *(const LAS bf16x8*)(lds + PG8_SB(b, h) + boff + n * 2048 + k * 1024); } while (0)
; #define PG8_MMA(ai, bj, At, Bt) do { __builtin_amdgcn_s_setprio(1); _Pragma("unroll") for (int m = 0; m < 4; ++m) _Pragma("unroll") for (int n = 0; n < 2; ++n) _Pragma("unroll") for (int k = 0; k < 2; ++k) \
;         acc[ai][bj][m][n] = __builtin_amdgcn_mfma_f32_16x16x32_bf16(Bt[n][k], At[m][k], acc[ai][bj][m][n], 0, 0, 0); __builtin_amdgcn_s_setprio(0); } while (0)
; #define PG8_WAIT_V(n) asm volatile("s_waitcnt vmcnt(" #n ")" ::: "memory")
; #define PG8_WAIT_L(n) asm volatile("s_waitcnt lgkmcnt(" #n ")" ::: "memory")
; #define PG8_BAR __builtin_amdgcn_s_barrier()
; #define PG8_SCHED __builtin_amdgcn_sched_barrier(0)
; template <class Epi, class Sched>
; __device__ __forceinline__ void gemm_phase(LAS unsigned char* lds, const Gemm g, const Sched S, const Epi E, const int tid) {
;     ...
;             PG8_WAIT_V(8); PG8_WAIT_L(0); PG8_BAR; PG8_MMA(1, 0, At, B0); PG8_MMA(1, 1, At, B1); PG8_BAR; PG8_SCHED;
;             PG8_LDB(B0, 1, 0); PG8_LDB(B1, 1, 1); PG8_SCHED; PG8_LDA(At, 1, 0); PG8_STAGE(PG8_SA(0, 1), a2 + hstepA, voffA);
;             PG8_WAIT_V(8); PG8_WAIT_L(0); PG8_BAR; PG8_MMA(0, 0, At, B0); PG8_MMA(0, 1, At, B1); PG8_BAR; PG8_SCHED;
	s_setprio 1
	v_mfma_f32_16x16x32_bf16 v[62:65], v[50:53], v[192:195], v[62:65]
	v_mfma_f32_16x16x32_bf16 v[58:61], v[150:153], v[192:195], v[58:61]
	v_mfma_f32_16x16x32_bf16 v[42:45], v[50:53], v[200:203], v[42:45]
	v_mfma_f32_16x16x32_bf16 v[38:41], v[150:153], v[200:203], v[38:41]
	v_mfma_f32_16x16x32_bf16 v[26:29], v[50:53], v[208:211], v[26:29]
	v_mfma_f32_16x16x32_bf16 v[22:25], v[150:153], v[208:211], v[22:25]
	v_mfma_f32_16x16x32_bf16 v[10:13], v[50:53], v[216:219], v[10:13]
	v_mfma_f32_16x16x32_bf16 v[6:9], v[150:153], v[216:219], v[6:9]
	v_mfma_f32_16x16x32_bf16 v[62:65], v[102:105], v[196:199], v[62:65]
	v_mfma_f32_16x16x32_bf16 v[58:61], v[154:157], v[196:199], v[58:61]
	v_mfma_f32_16x16x32_bf16 v[42:45], v[102:105], v[204:207], v[42:45]
	v_mfma_f32_16x16x32_bf16 v[38:41], v[154:157], v[204:207], v[38:41]
	v_mfma_f32_16x16x32_bf16 v[26:29], v[102:105], v[212:215], v[26:29]
	v_mfma_f32_16x16x32_bf16 v[22:25], v[154:157], v[212:215], v[22:25]
	v_mfma_f32_16x16x32_bf16 v[10:13], v[102:105], v[220:223], v[10:13]
	v_mfma_f32_16x16x32_bf16 v[6:9], v[154:157], v[220:223], v[6:9]
	v_mfma_f32_16x16x32_bf16 v[54:57], v[184:187], v[192:195], v[54:57]
	v_mfma_f32_16x16x32_bf16 v[46:49], v[158:161], v[200:203], v[46:49]
	v_mfma_f32_16x16x32_bf16 v[34:37], v[184:187], v[200:203], v[34:37]
	v_mfma_f32_16x16x32_bf16 v[30:33], v[158:161], v[208:211], v[30:33]
	v_mfma_f32_16x16x32_bf16 v[18:21], v[184:187], v[208:211], v[18:21]
	v_mfma_f32_16x16x32_bf16 v[14:17], v[158:161], v[216:219], v[14:17]
	v_mfma_f32_16x16x32_bf16 v[2:5], v[184:187], v[216:219], v[2:5]
	v_mfma_f32_16x16x32_bf16 v[50:53], v[158:161], v[192:195], v[66:69]
	v_mfma_f32_16x16x32_bf16 v[54:57], v[188:191], v[196:199], v[54:57]
	v_mfma_f32_16x16x32_bf16 v[46:49], v[180:183], v[204:207], v[46:49]
	v_mfma_f32_16x16x32_bf16 v[34:37], v[188:191], v[204:207], v[34:37]
	v_mfma_f32_16x16x32_bf16 v[30:33], v[180:183], v[212:215], v[30:33]
	v_mfma_f32_16x16x32_bf16 v[18:21], v[188:191], v[212:215], v[18:21]
	v_mfma_f32_16x16x32_bf16 v[14:17], v[180:183], v[220:223], v[14:17]
	v_mfma_f32_16x16x32_bf16 v[2:5], v[188:191], v[220:223], v[2:5]
	v_mfma_f32_16x16x32_bf16 v[50:53], v[180:183], v[196:199], v[50:53]
	s_setprio 0
	s_barrier
	s_add_i32 s83, 0, 0x18000
	s_add_i32 s84, 0, 0x1c000
	v_add_u32_e32 v154, s83, v165
	v_add_u32_e32 v167, s84, v165
	ds_read_b128 v[66:69], v154
	ds_read_b128 v[102:105], v154 offset:1024
	ds_read_b128 v[150:153], v154 offset:2048
	ds_read_b128 v[154:157], v154 offset:3072
	ds_read_b128 v[158:161], v167
	ds_read_b128 v[180:183], v167 offset:1024
	ds_read_b128 v[184:187], v167 offset:2048
	ds_read_b128 v[188:191], v167 offset:3072
	s_add_u32 s14, s14, 0x40000
	s_addc_u32 s15, s15, 0
	s_mov_b32 m0, s91
	v_lshl_add_u64 v[230:231], s[14:15], 0, v[138:139]
	ds_read_b128 v[192:195], v166 offset:32768
	ds_read_b128 v[196:199], v166 offset:33792
	ds_read_b128 v[200:203], v166 offset:34816
	ds_read_b128 v[204:207], v166 offset:35840
	ds_read_b128 v[208:211], v166 offset:36864
	ds_read_b128 v[212:215], v166 offset:37888
	ds_read_b128 v[216:219], v166 offset:38912
	ds_read_b128 v[220:223], v166 offset:39936
	global_load_lds_dwordx4 v[230:231], off
	v_lshl_add_u64 v[230:231], s[14:15], 0, v[142:143]
	s_mov_b32 m0, s68
	s_nop 0
	global_load_lds_dwordx4 v[230:231], off
	s_waitcnt vmcnt(8)
	s_waitcnt lgkmcnt(0)
	s_barrier
	s_setprio 1
	v_mfma_f32_16x16x32_bf16 v[130:133], v[66:69], v[192:195], v[130:133]
	v_mfma_f32_16x16x32_bf16 v[126:129], v[150:153], v[192:195], v[126:129]
	v_mfma_f32_16x16x32_bf16 v[114:117], v[66:69], v[200:203], v[114:117]
	v_mfma_f32_16x16x32_bf16 v[110:113], v[150:153], v[200:203], v[110:113]
	v_mfma_f32_16x16x32_bf16 v[94:97], v[66:69], v[208:211], v[94:97]
	v_mfma_f32_16x16x32_bf16 v[90:93], v[150:153], v[208:211], v[90:93]
	v_mfma_f32_16x16x32_bf16 v[78:81], v[66:69], v[216:219], v[78:81]
	v_mfma_f32_16x16x32_bf16 v[74:77], v[150:153], v[216:219], v[74:77]
	v_mfma_f32_16x16x32_bf16 v[130:133], v[102:105], v[196:199], v[130:133]
	v_mfma_f32_16x16x32_bf16 v[126:129], v[154:157], v[196:199], v[126:129]
	v_mfma_f32_16x16x32_bf16 v[114:117], v[102:105], v[204:207], v[114:117]
	v_mfma_f32_16x16x32_bf16 v[110:113], v[154:157], v[204:207], v[110:113]
	v_mfma_f32_16x16x32_bf16 v[94:97], v[102:105], v[212:215], v[94:97]
	v_mfma_f32_16x16x32_bf16 v[90:93], v[154:157], v[212:215], v[90:93]
	v_mfma_f32_16x16x32_bf16 v[78:81], v[102:105], v[220:223], v[78:81]
	v_mfma_f32_16x16x32_bf16 v[74:77], v[154:157], v[220:223], v[74:77]
	v_mfma_f32_16x16x32_bf16 v[134:137], v[158:161], v[192:195], v[134:137]
	v_mfma_f32_16x16x32_bf16 v[122:125], v[184:187], v[192:195], v[122:125]
	v_mfma_f32_16x16x32_bf16 v[118:121], v[158:161], v[200:203], v[118:121]
	v_mfma_f32_16x16x32_bf16 v[106:109], v[184:187], v[200:203], v[106:109]
	v_mfma_f32_16x16x32_bf16 v[98:101], v[158:161], v[208:211], v[98:101]
	v_mfma_f32_16x16x32_bf16 v[86:89], v[184:187], v[208:211], v[86:89]
	v_mfma_f32_16x16x32_bf16 v[82:85], v[158:161], v[216:219], v[82:85]
	v_mfma_f32_16x16x32_bf16 v[70:73], v[184:187], v[216:219], v[70:73]
	v_mfma_f32_16x16x32_bf16 v[134:137], v[180:183], v[196:199], v[134:137]
	v_mfma_f32_16x16x32_bf16 v[122:125], v[188:191], v[196:199], v[122:125]
	v_mfma_f32_16x16x32_bf16 v[118:121], v[180:183], v[204:207], v[118:121]
	v_mfma_f32_16x16x32_bf16 v[106:109], v[188:191], v[204:207], v[106:109]
	v_mfma_f32_16x16x32_bf16 v[98:101], v[180:183], v[212:215], v[98:101]
	v_mfma_f32_16x16x32_bf16 v[86:89], v[188:191], v[212:215], v[86:89]
	v_mfma_f32_16x16x32_bf16 v[82:85], v[180:183], v[220:223], v[82:85]
	v_mfma_f32_16x16x32_bf16 v[70:73], v[188:191], v[220:223], v[70:73]
	s_setprio 0
	s_barrier
; #define PG8_STAGE(bufoff, gbase, voff) do { _Pragma("unroll") for (int _i = 0; _i < 2; ++_i) \
;         __builtin_amdgcn_global_load_lds((const unsigned*)((const char*)(gbase) + (voff)[_i]), (LAS unsigned*)(lds + (bufoff) + ldsw + _i * 8192), 16, 0, 0); } while (0)
; #define PG8_LDA(dst, b, h) do { _Pragma("unroll") for (int m = 0; m < 4; ++m) _Pragma("unroll") for (int k = 0; k < 2; ++k) dst[m][k] = *(const LAS bf16x8*)(lds + PG8_SA(b, h) + aoff + m * 2048 + k * 1024); } while (0)
; #define PG8_MMA(ai, bj, At, Bt) do { __builtin_amdgcn_s_setprio(1); _Pragma("unroll") for (int m = 0; m < 4; ++m) _Pragma("unroll") for (int n = 0; n < 2; ++n) _Pragma("unroll") for (int k = 0; k < 2; ++k) \
;         acc[ai][bj][m][n] = __builtin_amdgcn_mfma_f32_16x16x32_bf16(Bt[n][k], At[m][k], acc[ai][bj][m][n], 0, 0, 0); __builtin_amdgcn_s_setprio(0); } while (0)
; #define PG8_WAIT_V(n) asm volatile("s_waitcnt vmcnt(" #n ")" ::: "memory")
; #define PG8_WAIT_L(n) asm volatile("s_waitcnt lgkmcnt(" #n ")" ::: "memory")
; #define PG8_BAR __builtin_amdgcn_s_barrier()
; #define PG8_SCHED __builtin_amdgcn_sched_barrier(0)
; template <class Epi, class Sched>
; __device__ __forceinline__ void gemm_phase(LAS unsigned char* lds, const Gemm g, const Sched S, const Epi E, const int tid) {
;     ...
;             PG8_LDA(At, 1, 1); PG8_STAGE(PG8_SB(1, 0), b3, voffB); PG8_STAGE(PG8_SB(1, 1), b3 + hstepB, voffB); PG8_STAGE(PG8_SA(1, 0), a3, voffA);
;             PG8_WAIT_V(8); PG8_WAIT_L(0); PG8_BAR; PG8_MMA(1, 0, At, B0); PG8_MMA(1, 1, At, B1); PG8_BAR; PG8_SCHED;
;         }
;         if (wr == 0) PG8_BAR;
	s_add_i32 s14, s83, s37
	v_lshl_add_u64 v[162:163], v[162:163], 0, s[64:65]
	s_mov_b32 m0, s14
	ds_read_b128 v[192:195], v166 offset:49152
	ds_read_b128 v[196:199], v166 offset:50176
	ds_read_b128 v[200:203], v166 offset:51200
	ds_read_b128 v[204:207], v166 offset:52224
	ds_read_b128 v[208:211], v166 offset:53248
	ds_read_b128 v[212:215], v166 offset:54272
	ds_read_b128 v[216:219], v166 offset:55296
	ds_read_b128 v[220:223], v166 offset:56320
	global_load_lds_dwordx4 v[162:163], off
	s_add_i32 m0, s14, 0x2000
	s_add_u32 s12, s12, 0x40080
	v_lshl_add_u64 v[162:163], v[224:225], 0, s[64:65]
	s_addc_u32 s13, s13, 0
	s_add_i32 s14, s84, s37
	global_load_lds_dwordx4 v[162:163], off
	v_lshl_add_u64 v[162:163], s[12:13], 0, v[140:141]
	s_mov_b32 m0, s14
	s_nop 0
	global_load_lds_dwordx4 v[162:163], off
	v_lshl_add_u64 v[162:163], s[12:13], 0, v[144:145]
	s_add_i32 m0, s14, 0x2000
	s_nop 0
	global_load_lds_dwordx4 v[162:163], off
	v_lshl_add_u64 v[162:163], v[226:227], 0, s[64:65]
	s_mov_b32 m0, s29
	s_nop 0
	global_load_lds_dwordx4 v[162:163], off
	v_lshl_add_u64 v[162:163], v[228:229], 0, s[64:65]
	s_mov_b32 m0, s92
	s_nop 0
	global_load_lds_dwordx4 v[162:163], off
	s_waitcnt vmcnt(8)
	s_waitcnt lgkmcnt(0)
	s_barrier
	s_setprio 1
	v_mfma_f32_16x16x32_bf16 v[62:65], v[66:69], v[192:195], v[62:65]
	v_mfma_f32_16x16x32_bf16 v[58:61], v[150:153], v[192:195], v[58:61]
	v_mfma_f32_16x16x32_bf16 v[42:45], v[66:69], v[200:203], v[42:45]
	v_mfma_f32_16x16x32_bf16 v[38:41], v[150:153], v[200:203], v[38:41]
	v_mfma_f32_16x16x32_bf16 v[26:29], v[66:69], v[208:211], v[26:29]
	v_mfma_f32_16x16x32_bf16 v[22:25], v[150:153], v[208:211], v[22:25]
	v_mfma_f32_16x16x32_bf16 v[10:13], v[66:69], v[216:219], v[10:13]
	v_mfma_f32_16x16x32_bf16 v[6:9], v[150:153], v[216:219], v[6:9]
	v_mfma_f32_16x16x32_bf16 v[62:65], v[102:105], v[196:199], v[62:65]
	v_mfma_f32_16x16x32_bf16 v[58:61], v[154:157], v[196:199], v[58:61]
	v_mfma_f32_16x16x32_bf16 v[42:45], v[102:105], v[204:207], v[42:45]
	v_mfma_f32_16x16x32_bf16 v[38:41], v[154:157], v[204:207], v[38:41]
	v_mfma_f32_16x16x32_bf16 v[26:29], v[102:105], v[212:215], v[26:29]
	v_mfma_f32_16x16x32_bf16 v[22:25], v[154:157], v[212:215], v[22:25]
	v_mfma_f32_16x16x32_bf16 v[10:13], v[102:105], v[220:223], v[10:13]
	v_mfma_f32_16x16x32_bf16 v[6:9], v[154:157], v[220:223], v[6:9]
	v_mfma_f32_16x16x32_bf16 v[50:53], v[158:161], v[192:195], v[50:53]
	v_mfma_f32_16x16x32_bf16 v[66:69], v[180:183], v[196:199], v[50:53]
	v_mfma_f32_16x16x32_bf16 v[50:53], v[184:187], v[192:195], v[54:57]
	v_mfma_f32_16x16x32_bf16 v[46:49], v[158:161], v[200:203], v[46:49]
	v_mfma_f32_16x16x32_bf16 v[34:37], v[184:187], v[200:203], v[34:37]
	v_mfma_f32_16x16x32_bf16 v[30:33], v[158:161], v[208:211], v[30:33]
	v_mfma_f32_16x16x32_bf16 v[18:21], v[184:187], v[208:211], v[18:21]
	v_mfma_f32_16x16x32_bf16 v[14:17], v[158:161], v[216:219], v[14:17]
	v_mfma_f32_16x16x32_bf16 v[2:5], v[184:187], v[216:219], v[2:5]
	v_mfma_f32_16x16x32_bf16 v[54:57], v[188:191], v[196:199], v[50:53]
	v_mfma_f32_16x16x32_bf16 v[46:49], v[180:183], v[204:207], v[46:49]
	v_mfma_f32_16x16x32_bf16 v[34:37], v[188:191], v[204:207], v[34:37]
	v_mfma_f32_16x16x32_bf16 v[30:33], v[180:183], v[212:215], v[30:33]
	v_mfma_f32_16x16x32_bf16 v[18:21], v[188:191], v[212:215], v[18:21]
	v_mfma_f32_16x16x32_bf16 v[14:17], v[180:183], v[220:223], v[14:17]
	v_mfma_f32_16x16x32_bf16 v[2:5], v[188:191], v[220:223], v[2:5]
	s_setprio 0
	s_barrier
	s_add_i32 s82, s82, 2
	s_add_u32 s49, s49, 0x100
	s_addc_u32 s62, s62, 0
	s_add_u32 s10, s10, 0x100
	s_addc_u32 s11, s11, 0
	s_cmp_gt_u32 s82, 13
	s_cbranch_scc0 .LBB0_471
	s_and_b64 vcc, exec, s[18:19]
	s_cbranch_vccz .LBB0_474
	s_barrier

; #define PG8_STAGE(bufoff, gbase, voff) do { _Pragma("unroll") for (int _i = 0; _i < 2; ++_i) \
;         __builtin_amdgcn_global_load_lds((const unsigned*)((const char*)(gbase) + (voff)[_i]), (LAS unsigned*)(lds + (bufoff) + ldsw + _i * 8192), 16, 0, 0); } while (0)
; #define PG8_LDA(dst, b, h) do { _Pragma("unroll") for (int m = 0; m < 4; ++m) _Pragma("unroll") for (int k = 0; k < 2; ++k) dst[m][k] = *(const LAS bf16x8*)(lds + PG8_SA(b, h) + aoff + m * 2048 + k * 1024); } while (0)
; #define PG8_LDB(dst, b, h) do { _Pragma("unroll") for (int n = 0; n < 2; ++n) _Pragma("unroll") for (int k = 0; k < 2; ++k) dst[n][k] = *(const LAS bf16x8*)(lds + PG8_SB(b, h) + boff + n * 2048 + k * 1024); } while (0)
; #define PG8_MMA(ai, bj, At, Bt) do { __builtin_amdgcn_s_setprio(1); _Pragma("unroll") for (int m = 0; m < 4; ++m) _Pragma("unroll") for (int n = 0; n < 2; ++n) _Pragma("unroll") for (int k = 0; k < 2; ++k) \
;         acc[ai][bj][m][n] = __builtin_amdgcn_mfma_f32_16x16x32_bf16(Bt[n][k], At[m][k], acc[ai][bj][m][n], 0, 0, 0); __builtin_amdgcn_s_setprio(0); } while (0)
; #define PG8_WAIT_V(n) asm volatile("s_waitcnt vmcnt(" #n ")" ::: "memory")
; #define PG8_WAIT_L(n) asm volatile("s_waitcnt lgkmcnt(" #n ")" ::: "memory")
; #define PG8_BAR __builtin_amdgcn_s_barrier()
; #define PG8_SCHED __builtin_amdgcn_sched_barrier(0)
; template <class Epi, class Sched>
; __device__ __forceinline__ void gemm_phase(LAS unsigned char* lds, const Gemm g, const Sched S, const Epi E, const int tid) {
;     ...
;             const bool last = (t == nt - 2);
;             const char* a1 = cA + (size_t)(t + 1) * kstep;
;             const char* a2 = last ? nA : cA + (size_t)(t + 2) * kstep; const char* b2 = last ? nB : cB + (size_t)(t + 2) * kstep;
;             const char* a3 = a2 + kstep; const char* b3 = b2 + kstep;
;             PG8_LDB(B0, 0, 0); PG8_LDB(B1, 0, 1); PG8_SCHED; PG8_LDA(At, 0, 0); PG8_STAGE(PG8_SA(1, 1), a1 + hstepA, voffA);
;             PG8_WAIT_V(8); PG8_WAIT_L(0); PG8_BAR; PG8_MMA(0, 0, At, B0); PG8_MMA(0, 1, At, B1); PG8_BAR; PG8_SCHED;
;             PG8_LDA(At, 0, 1); PG8_STAGE(PG8_SB(0, 0), b2, voffB); PG8_STAGE(PG8_SB(0, 1), b2 + hstepB, voffB); PG8_STAGE(PG8_SA(0, 0), a2, voffA);
;             PG8_WAIT_V(8); PG8_WAIT_L(0); PG8_BAR; PG8_MMA(1, 0, At, B0); PG8_MMA(1, 1, At, B1); PG8_BAR; PG8_SCHED;
.LBB0_778:
	s_add_i32 s94, s20, 2
	s_add_u32 s95, s18, 0x80
	s_addc_u32 s21, s19, 0
	s_add_i32 vcc_lo, 0, 0x10000
	s_cmp_eq_u32 s69, s20
	s_cselect_b32 s21, s9, s21
	s_cselect_b32 s20, s8, s95
	s_cselect_b32 s97, s17, s93
	s_cselect_b32 s96, s16, s92
	s_add_i32 s95, 0, 0x14000
	v_add_u32_e32 v142, vcc_lo, v198
	v_add_u32_e32 v167, s95, v198
	ds_read_b128 v[126:129], v142
	ds_read_b128 v[134:137], v142 offset:1024
	ds_read_b128 v[138:141], v142 offset:2048
	ds_read_b128 v[142:145], v142 offset:3072
	ds_read_b128 v[146:149], v167
	ds_read_b128 v[150:153], v167 offset:1024
	ds_read_b128 v[154:157], v167 offset:2048
	ds_read_b128 v[186:189], v167 offset:3072
	v_lshl_add_u64 v[224:225], s[18:19], 0, v[184:185]
	s_add_i32 m0, s37, 0xc000
	ds_read_b128 v[190:193], v199
	ds_read_b128 v[194:197], v199 offset:1024
	ds_read_b128 v[200:203], v199 offset:2048
	ds_read_b128 v[204:207], v199 offset:3072
	ds_read_b128 v[208:211], v199 offset:4096
	ds_read_b128 v[212:215], v199 offset:5120
	ds_read_b128 v[216:219], v199 offset:6144
	ds_read_b128 v[220:223], v199 offset:7168
	global_load_lds_dwordx4 v[224:225], off
	v_lshl_add_u64 v[224:225], s[18:19], 0, v[182:183]
	s_add_i32 m0, s37, 0xe000
	s_nop 0
	global_load_lds_dwordx4 v[224:225], off
	s_waitcnt vmcnt(8)
	s_waitcnt lgkmcnt(0)
	s_barrier
	s_setprio 1
	v_mfma_f32_16x16x32_bf16 v[130:133], v[126:129], v[190:193], v[130:133]
	v_mfma_f32_16x16x32_bf16 v[122:125], v[138:141], v[190:193], v[122:125]
	v_mfma_f32_16x16x32_bf16 v[110:113], v[126:129], v[200:203], v[110:113]
	v_mfma_f32_16x16x32_bf16 v[106:109], v[138:141], v[200:203], v[106:109]
	v_mfma_f32_16x16x32_bf16 v[94:97], v[126:129], v[208:211], v[94:97]
	v_mfma_f32_16x16x32_bf16 v[90:93], v[138:141], v[208:211], v[90:93]
	v_mfma_f32_16x16x32_bf16 v[78:81], v[126:129], v[216:219], v[78:81]
	v_mfma_f32_16x16x32_bf16 v[74:77], v[138:141], v[216:219], v[74:77]
	v_mfma_f32_16x16x32_bf16 v[130:133], v[134:137], v[194:197], v[130:133]
	v_mfma_f32_16x16x32_bf16 v[122:125], v[142:145], v[194:197], v[122:125]
	v_mfma_f32_16x16x32_bf16 v[110:113], v[134:137], v[204:207], v[110:113]
	v_mfma_f32_16x16x32_bf16 v[106:109], v[142:145], v[204:207], v[106:109]
	v_mfma_f32_16x16x32_bf16 v[94:97], v[134:137], v[212:215], v[94:97]
	v_mfma_f32_16x16x32_bf16 v[90:93], v[142:145], v[212:215], v[90:93]
	v_mfma_f32_16x16x32_bf16 v[78:81], v[134:137], v[220:223], v[78:81]
	v_mfma_f32_16x16x32_bf16 v[74:77], v[142:145], v[220:223], v[74:77]
	v_mfma_f32_16x16x32_bf16 v[118:121], v[146:149], v[190:193], v[118:121]
	v_mfma_f32_16x16x32_bf16 v[114:117], v[154:157], v[190:193], v[114:117]
	v_mfma_f32_16x16x32_bf16 v[102:105], v[146:149], v[200:203], v[102:105]
	v_mfma_f32_16x16x32_bf16 v[98:101], v[154:157], v[200:203], v[98:101]
	v_mfma_f32_16x16x32_bf16 v[86:89], v[146:149], v[208:211], v[86:89]
	v_mfma_f32_16x16x32_bf16 v[82:85], v[154:157], v[208:211], v[82:85]
	v_mfma_f32_16x16x32_bf16 v[70:73], v[146:149], v[216:219], v[70:73]
	v_mfma_f32_16x16x32_bf16 v[66:69], v[154:157], v[216:219], v[66:69]
	v_mfma_f32_16x16x32_bf16 v[118:121], v[150:153], v[194:197], v[118:121]
	v_mfma_f32_16x16x32_bf16 v[114:117], v[186:189], v[194:197], v[114:117]
	v_mfma_f32_16x16x32_bf16 v[102:105], v[150:153], v[204:207], v[102:105]
	v_mfma_f32_16x16x32_bf16 v[98:101], v[186:189], v[204:207], v[98:101]
	v_mfma_f32_16x16x32_bf16 v[86:89], v[150:153], v[212:215], v[86:89]
	v_mfma_f32_16x16x32_bf16 v[82:85], v[186:189], v[212:215], v[82:85]
	v_mfma_f32_16x16x32_bf16 v[70:73], v[150:153], v[220:223], v[70:73]
	v_mfma_f32_16x16x32_bf16 v[66:69], v[186:189], v[220:223], v[66:69]
	s_setprio 0
	s_barrier
	s_add_i32 vcc_lo, vcc_lo, s29
	v_lshl_add_u64 v[224:225], s[96:97], 0, v[160:161]
	s_mov_b32 m0, vcc_lo
	ds_read_b128 v[190:193], v199 offset:16384
	ds_read_b128 v[194:197], v199 offset:17408
	ds_read_b128 v[200:203], v199 offset:18432
	ds_read_b128 v[204:207], v199 offset:19456
	ds_read_b128 v[208:211], v199 offset:20480
	ds_read_b128 v[212:215], v199 offset:21504
	ds_read_b128 v[216:219], v199 offset:22528
	ds_read_b128 v[220:223], v199 offset:23552
	global_load_lds_dwordx4 v[224:225], off
	s_add_i32 m0, vcc_lo, 0x2000
	v_lshl_add_u64 v[226:227], s[96:97], 0, v[164:165]
	s_add_u32 s96, s96, s62
	s_addc_u32 s97, s97, 0
	s_add_i32 s95, s95, s29
	global_load_lds_dwordx4 v[226:227], off
	v_lshl_add_u64 v[228:229], s[96:97], 0, v[160:161]
	s_mov_b32 m0, s95
	v_lshl_add_u64 v[230:231], s[96:97], 0, v[164:165]
	global_load_lds_dwordx4 v[228:229], off
	s_add_i32 m0, s95, 0x2000
	v_lshl_add_u64 v[232:233], s[20:21], 0, v[158:159]
	global_load_lds_dwordx4 v[230:231], off
	s_mov_b32 m0, s37
	v_lshl_add_u64 v[234:235], s[20:21], 0, v[162:163]
	global_load_lds_dwordx4 v[232:233], off
	s_mov_b32 m0, s40
	s_nop 0
	global_load_lds_dwordx4 v[234:235], off
	s_waitcnt vmcnt(8)
	s_waitcnt lgkmcnt(0)
	s_barrier
; #define PG8_STAGE(bufoff, gbase, voff) do { _Pragma("unroll") for (int _i = 0; _i < 2; ++_i) \
;         __builtin_amdgcn_global_load_lds((const unsigned*)((const char*)(gbase) + (voff)[_i]), (LAS unsigned*)(lds + (bufoff) + ldsw + _i * 8192), 16, 0, 0); } while (0)
; #define PG8_LDA(dst, b, h) do { _Pragma("unroll") for (int m = 0; m < 4; ++m) _Pragma("unroll") for (int k = 0; k < 2; ++k) dst[m][k] = *(const LAS bf16x8*)(lds + PG8_SA(b, h) + aoff + m * 2048 + k * 1024); } while (0)
; #define PG8_LDB(dst, b, h) do { _Pragma("unroll") for (int n = 0; n < 2; ++n) _Pragma("unroll") for (int k = 0; k < 2; ++k) dst[n][k] = *(const LAS bf16x8*)(lds + PG8_SB(b, h) + boff + n * 2048 + k * 1024); } while (0)
; #define PG8_MMA(ai, bj, At, Bt) do { __builtin_amdgcn_s_setprio(1); _Pragma("unroll") for (int m = 0; m < 4; ++m) _Pragma("unroll") for (int n = 0; n < 2; ++n) _Pragma("unroll") for (int k = 0; k < 2; ++k) \
;         acc[ai][bj][m][n] = __builtin_amdgcn_mfma_f32_16x16x32_bf16(Bt[n][k], At[m][k], acc[ai][bj][m][n], 0, 0, 0); __builtin_amdgcn_s_setprio(0); } while (0)
; #define PG8_WAIT_V(n) asm volatile("s_waitcnt vmcnt(" #n ")" ::: "memory")
; #define PG8_WAIT_L(n) asm volatile("s_waitcnt lgkmcnt(" #n ")" ::: "memory")
; #define PG8_BAR __builtin_amdgcn_s_barrier()
; #define PG8_SCHED __builtin_amdgcn_sched_barrier(0)
; template <class Epi, class Sched>
; __device__ __forceinline__ void gemm_phase(LAS unsigned char* lds, const Gemm g, const Sched S, const Epi E, const int tid) {
;     ...
;             PG8_WAIT_V(8); PG8_WAIT_L(0); PG8_BAR; PG8_MMA(1, 0, At, B0); PG8_MMA(1, 1, At, B1); PG8_BAR; PG8_SCHED;
;             PG8_LDB(B0, 1, 0); PG8_LDB(B1, 1, 1); PG8_SCHED; PG8_LDA(At, 1, 0); PG8_STAGE(PG8_SA(0, 1), a2 + hstepA, voffA);
;             PG8_WAIT_V(8); PG8_WAIT_L(0); PG8_BAR; PG8_MMA(0, 0, At, B0); PG8_MMA(0, 1, At, B1); PG8_BAR; PG8_SCHED;
	s_setprio 1
	v_mfma_f32_16x16x32_bf16 v[62:65], v[126:129], v[190:193], v[62:65]
	v_mfma_f32_16x16x32_bf16 v[58:61], v[138:141], v[190:193], v[58:61]
	v_mfma_f32_16x16x32_bf16 v[46:49], v[126:129], v[200:203], v[46:49]
	v_mfma_f32_16x16x32_bf16 v[42:45], v[138:141], v[200:203], v[42:45]
	v_mfma_f32_16x16x32_bf16 v[30:33], v[126:129], v[208:211], v[30:33]
	v_mfma_f32_16x16x32_bf16 v[26:29], v[138:141], v[208:211], v[26:29]
	v_mfma_f32_16x16x32_bf16 v[14:17], v[126:129], v[216:219], v[14:17]
	v_mfma_f32_16x16x32_bf16 v[10:13], v[138:141], v[216:219], v[10:13]
	v_mfma_f32_16x16x32_bf16 v[62:65], v[134:137], v[194:197], v[62:65]
	v_mfma_f32_16x16x32_bf16 v[58:61], v[142:145], v[194:197], v[58:61]
	v_mfma_f32_16x16x32_bf16 v[46:49], v[134:137], v[204:207], v[46:49]
	v_mfma_f32_16x16x32_bf16 v[42:45], v[142:145], v[204:207], v[42:45]
	v_mfma_f32_16x16x32_bf16 v[30:33], v[134:137], v[212:215], v[30:33]
	v_mfma_f32_16x16x32_bf16 v[26:29], v[142:145], v[212:215], v[26:29]
	v_mfma_f32_16x16x32_bf16 v[14:17], v[134:137], v[220:223], v[14:17]
	v_mfma_f32_16x16x32_bf16 v[10:13], v[142:145], v[220:223], v[10:13]
	v_mfma_f32_16x16x32_bf16 v[54:57], v[146:149], v[190:193], v[54:57]
	v_mfma_f32_16x16x32_bf16 v[50:53], v[154:157], v[190:193], v[50:53]
	v_mfma_f32_16x16x32_bf16 v[38:41], v[146:149], v[200:203], v[38:41]
	v_mfma_f32_16x16x32_bf16 v[34:37], v[154:157], v[200:203], v[34:37]
	v_mfma_f32_16x16x32_bf16 v[22:25], v[146:149], v[208:211], v[22:25]
	v_mfma_f32_16x16x32_bf16 v[18:21], v[154:157], v[208:211], v[18:21]
	v_mfma_f32_16x16x32_bf16 v[6:9], v[146:149], v[216:219], v[6:9]
	v_mfma_f32_16x16x32_bf16 v[2:5], v[154:157], v[216:219], v[2:5]
	v_mfma_f32_16x16x32_bf16 v[54:57], v[150:153], v[194:197], v[54:57]
	v_mfma_f32_16x16x32_bf16 v[50:53], v[186:189], v[194:197], v[50:53]
	v_mfma_f32_16x16x32_bf16 v[38:41], v[150:153], v[204:207], v[38:41]
	v_mfma_f32_16x16x32_bf16 v[34:37], v[186:189], v[204:207], v[34:37]
	v_mfma_f32_16x16x32_bf16 v[22:25], v[150:153], v[212:215], v[22:25]
	v_mfma_f32_16x16x32_bf16 v[18:21], v[186:189], v[212:215], v[18:21]
	v_mfma_f32_16x16x32_bf16 v[6:9], v[150:153], v[220:223], v[6:9]
	v_mfma_f32_16x16x32_bf16 v[2:5], v[186:189], v[220:223], v[2:5]
	s_setprio 0
	s_barrier
	s_add_i32 s95, 0, 0x18000
	s_add_i32 s96, 0, 0x1c000
	v_add_u32_e32 v142, s95, v198
	v_add_u32_e32 v167, s96, v198
	ds_read_b128 v[126:129], v142
	ds_read_b128 v[134:137], v142 offset:1024
	ds_read_b128 v[138:141], v142 offset:2048
	ds_read_b128 v[142:145], v142 offset:3072
	ds_read_b128 v[146:149], v167
	ds_read_b128 v[150:153], v167 offset:1024
	ds_read_b128 v[154:157], v167 offset:2048
	ds_read_b128 v[186:189], v167 offset:3072
	s_add_u32 s20, s20, s62
	s_addc_u32 s21, s21, 0
	s_mov_b32 m0, s41
	v_lshl_add_u64 v[246:247], s[20:21], 0, v[158:159]
	ds_read_b128 v[190:193], v199 offset:32768
	ds_read_b128 v[194:197], v199 offset:33792
	ds_read_b128 v[200:203], v199 offset:34816
	ds_read_b128 v[204:207], v199 offset:35840
	ds_read_b128 v[208:211], v199 offset:36864
	ds_read_b128 v[212:215], v199 offset:37888
	ds_read_b128 v[216:219], v199 offset:38912
	ds_read_b128 v[220:223], v199 offset:39936
	global_load_lds_dwordx4 v[246:247], off
	v_lshl_add_u64 v[246:247], s[20:21], 0, v[162:163]
	s_mov_b32 m0, s42
	s_nop 0
	global_load_lds_dwordx4 v[246:247], off
	s_waitcnt vmcnt(8)
	s_waitcnt lgkmcnt(0)
	s_barrier
	s_setprio 1
	v_mfma_f32_16x16x32_bf16 v[130:133], v[126:129], v[190:193], v[130:133]
	v_mfma_f32_16x16x32_bf16 v[122:125], v[138:141], v[190:193], v[122:125]
	v_mfma_f32_16x16x32_bf16 v[110:113], v[126:129], v[200:203], v[110:113]
	v_mfma_f32_16x16x32_bf16 v[106:109], v[138:141], v[200:203], v[106:109]
	v_mfma_f32_16x16x32_bf16 v[94:97], v[126:129], v[208:211], v[94:97]
	v_mfma_f32_16x16x32_bf16 v[90:93], v[138:141], v[208:211], v[90:93]
	v_mfma_f32_16x16x32_bf16 v[78:81], v[126:129], v[216:219], v[78:81]
	v_mfma_f32_16x16x32_bf16 v[74:77], v[138:141], v[216:219], v[74:77]
	v_mfma_f32_16x16x32_bf16 v[130:133], v[134:137], v[194:197], v[130:133]
	v_mfma_f32_16x16x32_bf16 v[122:125], v[142:145], v[194:197], v[122:125]
	v_mfma_f32_16x16x32_bf16 v[110:113], v[134:137], v[204:207], v[110:113]
	v_mfma_f32_16x16x32_bf16 v[106:109], v[142:145], v[204:207], v[106:109]
	v_mfma_f32_16x16x32_bf16 v[94:97], v[134:137], v[212:215], v[94:97]
	v_mfma_f32_16x16x32_bf16 v[90:93], v[142:145], v[212:215], v[90:93]
	v_mfma_f32_16x16x32_bf16 v[78:81], v[134:137], v[220:223], v[78:81]
	v_mfma_f32_16x16x32_bf16 v[74:77], v[142:145], v[220:223], v[74:77]
	v_mfma_f32_16x16x32_bf16 v[118:121], v[146:149], v[190:193], v[118:121]
	v_mfma_f32_16x16x32_bf16 v[114:117], v[154:157], v[190:193], v[114:117]
	v_mfma_f32_16x16x32_bf16 v[102:105], v[146:149], v[200:203], v[102:105]
	v_mfma_f32_16x16x32_bf16 v[98:101], v[154:157], v[200:203], v[98:101]
	v_mfma_f32_16x16x32_bf16 v[86:89], v[146:149], v[208:211], v[86:89]
	v_mfma_f32_16x16x32_bf16 v[82:85], v[154:157], v[208:211], v[82:85]
	v_mfma_f32_16x16x32_bf16 v[70:73], v[146:149], v[216:219], v[70:73]
	v_mfma_f32_16x16x32_bf16 v[66:69], v[154:157], v[216:219], v[66:69]
	v_mfma_f32_16x16x32_bf16 v[118:121], v[150:153], v[194:197], v[118:121]
	v_mfma_f32_16x16x32_bf16 v[114:117], v[186:189], v[194:197], v[114:117]
	v_mfma_f32_16x16x32_bf16 v[102:105], v[150:153], v[204:207], v[102:105]
	v_mfma_f32_16x16x32_bf16 v[98:101], v[186:189], v[204:207], v[98:101]
	v_mfma_f32_16x16x32_bf16 v[86:89], v[150:153], v[212:215], v[86:89]
	v_mfma_f32_16x16x32_bf16 v[82:85], v[186:189], v[212:215], v[82:85]
	v_mfma_f32_16x16x32_bf16 v[70:73], v[150:153], v[220:223], v[70:73]
	v_mfma_f32_16x16x32_bf16 v[66:69], v[186:189], v[220:223], v[66:69]
	s_setprio 0
	s_barrier
; #define PG8_STAGE(bufoff, gbase, voff) do { _Pragma("unroll") for (int _i = 0; _i < 2; ++_i) \
;         __builtin_amdgcn_global_load_lds((const unsigned*)((const char*)(gbase) + (voff)[_i]), (LAS unsigned*)(lds + (bufoff) + ldsw + _i * 8192), 16, 0, 0); } while (0)
; #define PG8_LDA(dst, b, h) do { _Pragma("unroll") for (int m = 0; m < 4; ++m) _Pragma("unroll") for (int k = 0; k < 2; ++k) dst[m][k] = *(const LAS bf16x8*)(lds + PG8_SA(b, h) + aoff + m * 2048 + k * 1024); } while (0)
; #define PG8_MMA(ai, bj, At, Bt) do { __builtin_amdgcn_s_setprio(1); _Pragma("unroll") for (int m = 0; m < 4; ++m) _Pragma("unroll") for (int n = 0; n < 2; ++n) _Pragma("unroll") for (int k = 0; k < 2; ++k) \
;         acc[ai][bj][m][n] = __builtin_amdgcn_mfma_f32_16x16x32_bf16(Bt[n][k], At[m][k], acc[ai][bj][m][n], 0, 0, 0); __builtin_amdgcn_s_setprio(0); } while (0)
; #define PG8_WAIT_V(n) asm volatile("s_waitcnt vmcnt(" #n ")" ::: "memory")
; #define PG8_WAIT_L(n) asm volatile("s_waitcnt lgkmcnt(" #n ")" ::: "memory")
; #define PG8_BAR __builtin_amdgcn_s_barrier()
; #define PG8_SCHED __builtin_amdgcn_sched_barrier(0)
; template <class Epi, class Sched>
; __device__ __forceinline__ void gemm_phase(LAS unsigned char* lds, const Gemm g, const Sched S, const Epi E, const int tid) {
;     ...
;             PG8_LDA(At, 1, 1); PG8_STAGE(PG8_SB(1, 0), b3, voffB); PG8_STAGE(PG8_SB(1, 1), b3 + hstepB, voffB); PG8_STAGE(PG8_SA(1, 0), a3, voffA);
;             PG8_WAIT_V(8); PG8_WAIT_L(0); PG8_BAR; PG8_MMA(1, 0, At, B0); PG8_MMA(1, 1, At, B1); PG8_BAR; PG8_SCHED;
;         }
;         if (wr == 0) PG8_BAR;
	s_add_i32 s20, s95, s29
	v_lshl_add_u64 v[224:225], v[224:225], 0, s[64:65]
	s_mov_b32 m0, s20
	ds_read_b128 v[190:193], v199 offset:49152
	ds_read_b128 v[194:197], v199 offset:50176
	ds_read_b128 v[200:203], v199 offset:51200
	ds_read_b128 v[204:207], v199 offset:52224
	ds_read_b128 v[208:211], v199 offset:53248
	ds_read_b128 v[212:215], v199 offset:54272
	ds_read_b128 v[216:219], v199 offset:55296
	ds_read_b128 v[220:223], v199 offset:56320
	global_load_lds_dwordx4 v[224:225], off
	v_lshl_add_u64 v[224:225], v[226:227], 0, s[64:65]
	s_add_i32 m0, s20, 0x2000
	s_add_i32 s20, s96, s29
	global_load_lds_dwordx4 v[224:225], off
	v_lshl_add_u64 v[224:225], v[228:229], 0, s[64:65]
	s_mov_b32 m0, s20
	s_nop 0
	global_load_lds_dwordx4 v[224:225], off
	v_lshl_add_u64 v[224:225], v[230:231], 0, s[64:65]
	s_add_i32 m0, s20, 0x2000
	s_nop 0
	global_load_lds_dwordx4 v[224:225], off
	v_lshl_add_u64 v[224:225], v[232:233], 0, s[64:65]
	s_mov_b32 m0, s45
	s_nop 0
	global_load_lds_dwordx4 v[224:225], off
	v_lshl_add_u64 v[224:225], v[234:235], 0, s[64:65]
	s_mov_b32 m0, s46
	s_nop 0
	global_load_lds_dwordx4 v[224:225], off
	s_waitcnt vmcnt(8)
	s_waitcnt lgkmcnt(0)
	s_barrier
	s_setprio 1
	v_mfma_f32_16x16x32_bf16 v[62:65], v[126:129], v[190:193], v[62:65]
	v_mfma_f32_16x16x32_bf16 v[58:61], v[138:141], v[190:193], v[58:61]
	v_mfma_f32_16x16x32_bf16 v[46:49], v[126:129], v[200:203], v[46:49]
	v_mfma_f32_16x16x32_bf16 v[42:45], v[138:141], v[200:203], v[42:45]
	v_mfma_f32_16x16x32_bf16 v[30:33], v[126:129], v[208:211], v[30:33]
	v_mfma_f32_16x16x32_bf16 v[26:29], v[138:141], v[208:211], v[26:29]
	v_mfma_f32_16x16x32_bf16 v[14:17], v[126:129], v[216:219], v[14:17]
	v_mfma_f32_16x16x32_bf16 v[10:13], v[138:141], v[216:219], v[10:13]
	v_mfma_f32_16x16x32_bf16 v[62:65], v[134:137], v[194:197], v[62:65]
	v_mfma_f32_16x16x32_bf16 v[58:61], v[142:145], v[194:197], v[58:61]
	v_mfma_f32_16x16x32_bf16 v[46:49], v[134:137], v[204:207], v[46:49]
	v_mfma_f32_16x16x32_bf16 v[42:45], v[142:145], v[204:207], v[42:45]
	v_mfma_f32_16x16x32_bf16 v[30:33], v[134:137], v[212:215], v[30:33]
	v_mfma_f32_16x16x32_bf16 v[26:29], v[142:145], v[212:215], v[26:29]
	v_mfma_f32_16x16x32_bf16 v[14:17], v[134:137], v[220:223], v[14:17]
	v_mfma_f32_16x16x32_bf16 v[10:13], v[142:145], v[220:223], v[10:13]
	v_mfma_f32_16x16x32_bf16 v[54:57], v[146:149], v[190:193], v[54:57]
	v_mfma_f32_16x16x32_bf16 v[50:53], v[154:157], v[190:193], v[50:53]
	v_mfma_f32_16x16x32_bf16 v[38:41], v[146:149], v[200:203], v[38:41]
	v_mfma_f32_16x16x32_bf16 v[34:37], v[154:157], v[200:203], v[34:37]
	v_mfma_f32_16x16x32_bf16 v[22:25], v[146:149], v[208:211], v[22:25]
	v_mfma_f32_16x16x32_bf16 v[18:21], v[154:157], v[208:211], v[18:21]
	v_mfma_f32_16x16x32_bf16 v[6:9], v[146:149], v[216:219], v[6:9]
	v_mfma_f32_16x16x32_bf16 v[2:5], v[154:157], v[216:219], v[2:5]
	v_mfma_f32_16x16x32_bf16 v[54:57], v[150:153], v[194:197], v[54:57]
	v_mfma_f32_16x16x32_bf16 v[50:53], v[186:189], v[194:197], v[50:53]
	v_mfma_f32_16x16x32_bf16 v[38:41], v[150:153], v[204:207], v[38:41]
	v_mfma_f32_16x16x32_bf16 v[34:37], v[186:189], v[204:207], v[34:37]
	v_mfma_f32_16x16x32_bf16 v[22:25], v[150:153], v[212:215], v[22:25]
	v_mfma_f32_16x16x32_bf16 v[18:21], v[186:189], v[212:215], v[18:21]
	v_mfma_f32_16x16x32_bf16 v[6:9], v[150:153], v[220:223], v[6:9]
	v_mfma_f32_16x16x32_bf16 v[2:5], v[186:189], v[220:223], v[2:5]
	s_setprio 0
	s_barrier
	s_add_u32 s92, s92, 0x100
	s_addc_u32 s93, s93, 0
	s_add_u32 s18, s18, 0x100
	s_addc_u32 s19, s19, 0
	s_cmp_ge_u32 s94, s47
	s_mov_b32 s20, s94
	s_cbranch_scc0 .LBB0_778
	s_and_b64 vcc, exec, s[12:13]
	s_cbranch_vccz .LBB0_781
	s_barrier

; #define PG8_STAGE(bufoff, gbase, voff) do { _Pragma("unroll") for (int _i = 0; _i < 2; ++_i) \
;         __builtin_amdgcn_global_load_lds((const unsigned*)((const char*)(gbase) + (voff)[_i]), (LAS unsigned*)(lds + (bufoff) + ldsw + _i * 8192), 16, 0, 0); } while (0)
; #define PG8_LDA(dst, b, h) do { _Pragma("unroll") for (int m = 0; m < 4; ++m) _Pragma("unroll") for (int k = 0; k < 2; ++k) dst[m][k] = *(const LAS bf16x8*)(lds + PG8_SA(b, h) + aoff + m * 2048 + k * 1024); } while (0)
; #define PG8_LDB(dst, b, h) do { _Pragma("unroll") for (int n = 0; n < 2; ++n) _Pragma("unroll") for (int k = 0; k < 2; ++k) dst[n][k] = *(const LAS bf16x8*)(lds + PG8_SB(b, h) + boff + n * 2048 + k * 1024); } while (0)
; #define PG8_MMA(ai, bj, At, Bt) do { __builtin_amdgcn_s_setprio(1); _Pragma("unroll") for (int m = 0; m < 4; ++m) _Pragma("unroll") for (int n = 0; n < 2; ++n) _Pragma("unroll") for (int k = 0; k < 2; ++k) \
;         acc[ai][bj][m][n] = __builtin_amdgcn_mfma_f32_16x16x32_bf16(Bt[n][k], At[m][k], acc[ai][bj][m][n], 0, 0, 0); __builtin_amdgcn_s_setprio(0); } while (0)
; #define PG8_WAIT_V(n) asm volatile("s_waitcnt vmcnt(" #n ")" ::: "memory")
; #define PG8_WAIT_L(n) asm volatile("s_waitcnt lgkmcnt(" #n ")" ::: "memory")
; #define PG8_BAR __builtin_amdgcn_s_barrier()
; #define PG8_SCHED __builtin_amdgcn_sched_barrier(0)
; template <class Epi, class Sched>
; __device__ __forceinline__ void gemm_phase(LAS unsigned char* lds, const Gemm g, const Sched S, const Epi E, const int tid) {
;     ...
;             const bool last = (t == nt - 2);
;             const char* a1 = cA + (size_t)(t + 1) * kstep;
;             const char* a2 = last ? nA : cA + (size_t)(t + 2) * kstep; const char* b2 = last ? nB : cB + (size_t)(t + 2) * kstep;
;             const char* a3 = a2 + kstep; const char* b3 = b2 + kstep;
;             PG8_LDB(B0, 0, 0); PG8_LDB(B1, 0, 1); PG8_SCHED; PG8_LDA(At, 0, 0); PG8_STAGE(PG8_SA(1, 1), a1 + hstepA, voffA);
;             PG8_WAIT_V(8); PG8_WAIT_L(0); PG8_BAR; PG8_MMA(0, 0, At, B0); PG8_MMA(0, 1, At, B1); PG8_BAR; PG8_SCHED;
;             PG8_LDA(At, 0, 1); PG8_STAGE(PG8_SB(0, 0), b2, voffB); PG8_STAGE(PG8_SB(0, 1), b2 + hstepB, voffB); PG8_STAGE(PG8_SA(0, 0), a2, voffA);
;             PG8_WAIT_V(8); PG8_WAIT_L(0); PG8_BAR; PG8_MMA(1, 0, At, B0); PG8_MMA(1, 1, At, B1); PG8_BAR; PG8_SCHED;
.LBB0_819:
	s_add_u32 s24, s22, 0xfffc0080
	s_addc_u32 s25, s23, -1
	s_add_i32 s85, 0, 0x10000
	s_cmp_eq_u32 s84, 12
	s_cselect_b32 s27, s9, s25
	s_cselect_b32 s26, s17, s24
	s_cselect_b32 s25, s15, s83
	s_cselect_b32 s24, s69, s82
	s_add_i32 s90, 0, 0x14000
	v_add_u32_e32 v154, s85, v165
	v_add_u32_e32 v162, s90, v165
	ds_read_b128 v[98:101], v154
	ds_read_b128 v[134:137], v154 offset:1024
	ds_read_b128 v[150:153], v154 offset:2048
	ds_read_b128 v[154:157], v154 offset:3072
	ds_read_b128 v[158:161], v162
	ds_read_b128 v[180:183], v162 offset:1024
	ds_read_b128 v[184:187], v162 offset:2048
	ds_read_b128 v[188:191], v162 offset:3072
	v_lshl_add_u64 v[162:163], s[22:23], 0, v[148:149]
	s_add_i32 m0, s40, 0xc000
	ds_read_b128 v[192:195], v166
	ds_read_b128 v[196:199], v166 offset:1024
	ds_read_b128 v[200:203], v166 offset:2048
	ds_read_b128 v[204:207], v166 offset:3072
	ds_read_b128 v[208:211], v166 offset:4096
	ds_read_b128 v[212:215], v166 offset:5120
	ds_read_b128 v[216:219], v166 offset:6144
	ds_read_b128 v[220:223], v166 offset:7168
	global_load_lds_dwordx4 v[162:163], off
	v_lshl_add_u64 v[162:163], s[22:23], 0, v[146:147]
	s_add_i32 m0, s40, 0xe000
	s_nop 0
	global_load_lds_dwordx4 v[162:163], off
	s_waitcnt vmcnt(8)
	s_waitcnt lgkmcnt(0)
	s_barrier
	s_setprio 1
	v_mfma_f32_16x16x32_bf16 v[130:133], v[98:101], v[192:195], v[130:133]
	v_mfma_f32_16x16x32_bf16 v[118:121], v[150:153], v[192:195], v[118:121]
	v_mfma_f32_16x16x32_bf16 v[114:117], v[98:101], v[200:203], v[114:117]
	v_mfma_f32_16x16x32_bf16 v[102:105], v[150:153], v[200:203], v[102:105]
	v_mfma_f32_16x16x32_bf16 v[94:97], v[98:101], v[208:211], v[94:97]
	v_mfma_f32_16x16x32_bf16 v[82:85], v[150:153], v[208:211], v[82:85]
	v_mfma_f32_16x16x32_bf16 v[78:81], v[98:101], v[216:219], v[78:81]
	v_mfma_f32_16x16x32_bf16 v[66:69], v[150:153], v[216:219], v[66:69]
	v_mfma_f32_16x16x32_bf16 v[130:133], v[134:137], v[196:199], v[130:133]
	v_mfma_f32_16x16x32_bf16 v[118:121], v[154:157], v[196:199], v[118:121]
	v_mfma_f32_16x16x32_bf16 v[114:117], v[134:137], v[204:207], v[114:117]
	v_mfma_f32_16x16x32_bf16 v[102:105], v[154:157], v[204:207], v[102:105]
	v_mfma_f32_16x16x32_bf16 v[94:97], v[134:137], v[212:215], v[94:97]
	v_mfma_f32_16x16x32_bf16 v[82:85], v[154:157], v[212:215], v[82:85]
	v_mfma_f32_16x16x32_bf16 v[78:81], v[134:137], v[220:223], v[78:81]
	v_mfma_f32_16x16x32_bf16 v[66:69], v[154:157], v[220:223], v[66:69]
	v_mfma_f32_16x16x32_bf16 v[126:129], v[158:161], v[192:195], v[126:129]
	v_mfma_f32_16x16x32_bf16 v[122:125], v[184:187], v[192:195], v[122:125]
	v_mfma_f32_16x16x32_bf16 v[110:113], v[158:161], v[200:203], v[110:113]
	v_mfma_f32_16x16x32_bf16 v[106:109], v[184:187], v[200:203], v[106:109]
	v_mfma_f32_16x16x32_bf16 v[90:93], v[158:161], v[208:211], v[90:93]
	v_mfma_f32_16x16x32_bf16 v[86:89], v[184:187], v[208:211], v[86:89]
	v_mfma_f32_16x16x32_bf16 v[74:77], v[158:161], v[216:219], v[74:77]
	v_mfma_f32_16x16x32_bf16 v[70:73], v[184:187], v[216:219], v[70:73]
	v_mfma_f32_16x16x32_bf16 v[126:129], v[180:183], v[196:199], v[126:129]
	v_mfma_f32_16x16x32_bf16 v[122:125], v[188:191], v[196:199], v[122:125]
	v_mfma_f32_16x16x32_bf16 v[110:113], v[180:183], v[204:207], v[110:113]
	v_mfma_f32_16x16x32_bf16 v[106:109], v[188:191], v[204:207], v[106:109]
	v_mfma_f32_16x16x32_bf16 v[90:93], v[180:183], v[212:215], v[90:93]
	v_mfma_f32_16x16x32_bf16 v[86:89], v[188:191], v[212:215], v[86:89]
	v_mfma_f32_16x16x32_bf16 v[74:77], v[180:183], v[220:223], v[74:77]
	v_mfma_f32_16x16x32_bf16 v[70:73], v[188:191], v[220:223], v[70:73]
	s_setprio 0
	s_barrier
	s_add_i32 s85, s85, s28
	v_lshl_add_u64 v[162:163], s[24:25], 0, v[142:143]
	s_mov_b32 m0, s85
	ds_read_b128 v[192:195], v166 offset:16384
	ds_read_b128 v[196:199], v166 offset:17408
	ds_read_b128 v[200:203], v166 offset:18432
	ds_read_b128 v[204:207], v166 offset:19456
	ds_read_b128 v[208:211], v166 offset:20480
	ds_read_b128 v[212:215], v166 offset:21504
	ds_read_b128 v[216:219], v166 offset:22528
	ds_read_b128 v[220:223], v166 offset:23552
	global_load_lds_dwordx4 v[162:163], off
	s_add_i32 m0, s85, 0x2000
	s_add_u32 s88, s24, 0x40000
	v_lshl_add_u64 v[224:225], s[24:25], 0, v[138:139]
	s_addc_u32 s89, s25, 0
	s_add_i32 s85, s90, s28
	global_load_lds_dwordx4 v[224:225], off
	v_lshl_add_u64 v[226:227], s[88:89], 0, v[142:143]
	s_mov_b32 m0, s85
	v_lshl_add_u64 v[228:229], s[26:27], 0, v[140:141]
	global_load_lds_dwordx4 v[226:227], off
	v_lshl_add_u64 v[226:227], s[88:89], 0, v[138:139]
	s_add_i32 m0, s85, 0x2000
	s_nop 0
	global_load_lds_dwordx4 v[226:227], off
	v_lshl_add_u64 v[226:227], s[26:27], 0, v[144:145]
	s_mov_b32 m0, s40
	s_nop 0
	global_load_lds_dwordx4 v[226:227], off
	s_mov_b32 m0, s41
	s_nop 0
	global_load_lds_dwordx4 v[228:229], off
	s_waitcnt vmcnt(8)
	s_waitcnt lgkmcnt(0)
	s_barrier
; #define PG8_STAGE(bufoff, gbase, voff) do { _Pragma("unroll") for (int _i = 0; _i < 2; ++_i) \
;         __builtin_amdgcn_global_load_lds((const unsigned*)((const char*)(gbase) + (voff)[_i]), (LAS unsigned*)(lds + (bufoff) + ldsw + _i * 8192), 16, 0, 0); } while (0)
; #define PG8_LDA(dst, b, h) do { _Pragma("unroll") for (int m = 0; m < 4; ++m) _Pragma("unroll") for (int k = 0; k < 2; ++k) dst[m][k] = *(const LAS bf16x8*)(lds + PG8_SA(b, h) + aoff + m * 2048 + k * 1024); } while (0)
; #define PG8_LDB(dst, b, h) do { _Pragma("unroll") for (int n = 0; n < 2; ++n) _Pragma("unroll") for (int k = 0; k < 2; ++k) dst[n][k] = *(const LAS bf16x8*)(lds + PG8_SB(b, h) + boff + n * 2048 + k * 1024); } while (0)
; #define PG8_MMA(ai, bj, At, Bt) do { __builtin_amdgcn_s_setprio(1); _Pragma("unroll") for (int m = 0; m < 4; ++m) _Pragma("unroll") for (int n = 0; n < 2; ++n) _Pragma("unroll") for (int k = 0; k < 2; ++k) \
;         acc[ai][bj][m][n] = __builtin_amdgcn_mfma_f32_16x16x32_bf16(Bt[n][k], At[m][k], acc[ai][bj][m][n], 0, 0, 0); __builtin_amdgcn_s_setprio(0); } while (0)
; #define PG8_WAIT_V(n) asm volatile("s_waitcnt vmcnt(" #n ")" ::: "memory")
; #define PG8_WAIT_L(n) asm volatile("s_waitcnt lgkmcnt(" #n ")" ::: "memory")
; #define PG8_BAR __builtin_amdgcn_s_barrier()
; #define PG8_SCHED __builtin_amdgcn_sched_barrier(0)
; template <class Epi, class Sched>
; __device__ __forceinline__ void gemm_phase(LAS unsigned char* lds, const Gemm g, const Sched S, const Epi E, const int tid) {
;     ...
;             PG8_WAIT_V(8); PG8_WAIT_L(0); PG8_BAR; PG8_MMA(1, 0, At, B0); PG8_MMA(1, 1, At, B1); PG8_BAR; PG8_SCHED;
;             PG8_LDB(B0, 1, 0); PG8_LDB(B1, 1, 1); PG8_SCHED; PG8_LDA(At, 1, 0); PG8_STAGE(PG8_SA(0, 1), a2 + hstepA, voffA);
;             PG8_WAIT_V(8); PG8_WAIT_L(0); PG8_BAR; PG8_MMA(0, 0, At, B0); PG8_MMA(0, 1, At, B1); PG8_BAR; PG8_SCHED;
	s_setprio 1
	v_mfma_f32_16x16x32_bf16 v[62:65], v[98:101], v[192:195], v[62:65]
	v_mfma_f32_16x16x32_bf16 v[50:53], v[150:153], v[192:195], v[50:53]
	v_mfma_f32_16x16x32_bf16 v[46:49], v[98:101], v[200:203], v[46:49]
	v_mfma_f32_16x16x32_bf16 v[34:37], v[150:153], v[200:203], v[34:37]
	v_mfma_f32_16x16x32_bf16 v[30:33], v[98:101], v[208:211], v[30:33]
	v_mfma_f32_16x16x32_bf16 v[18:21], v[150:153], v[208:211], v[18:21]
	v_mfma_f32_16x16x32_bf16 v[14:17], v[98:101], v[216:219], v[14:17]
	v_mfma_f32_16x16x32_bf16 v[6:9], v[150:153], v[216:219], v[6:9]
	v_mfma_f32_16x16x32_bf16 v[62:65], v[134:137], v[196:199], v[62:65]
	v_mfma_f32_16x16x32_bf16 v[50:53], v[154:157], v[196:199], v[50:53]
	v_mfma_f32_16x16x32_bf16 v[46:49], v[134:137], v[204:207], v[46:49]
	v_mfma_f32_16x16x32_bf16 v[34:37], v[154:157], v[204:207], v[34:37]
	v_mfma_f32_16x16x32_bf16 v[30:33], v[134:137], v[212:215], v[30:33]
	v_mfma_f32_16x16x32_bf16 v[18:21], v[154:157], v[212:215], v[18:21]
	v_mfma_f32_16x16x32_bf16 v[14:17], v[134:137], v[220:223], v[14:17]
	v_mfma_f32_16x16x32_bf16 v[6:9], v[154:157], v[220:223], v[6:9]
	v_mfma_f32_16x16x32_bf16 v[58:61], v[158:161], v[192:195], v[58:61]
	v_mfma_f32_16x16x32_bf16 v[54:57], v[184:187], v[192:195], v[54:57]
	v_mfma_f32_16x16x32_bf16 v[42:45], v[158:161], v[200:203], v[42:45]
	v_mfma_f32_16x16x32_bf16 v[38:41], v[184:187], v[200:203], v[38:41]
	v_mfma_f32_16x16x32_bf16 v[26:29], v[158:161], v[208:211], v[26:29]
	v_mfma_f32_16x16x32_bf16 v[22:25], v[184:187], v[208:211], v[22:25]
	v_mfma_f32_16x16x32_bf16 v[10:13], v[158:161], v[216:219], v[10:13]
	v_mfma_f32_16x16x32_bf16 v[2:5], v[184:187], v[216:219], v[2:5]
	v_mfma_f32_16x16x32_bf16 v[58:61], v[180:183], v[196:199], v[58:61]
	v_mfma_f32_16x16x32_bf16 v[54:57], v[188:191], v[196:199], v[54:57]
	v_mfma_f32_16x16x32_bf16 v[42:45], v[180:183], v[204:207], v[42:45]
	v_mfma_f32_16x16x32_bf16 v[38:41], v[188:191], v[204:207], v[38:41]
	v_mfma_f32_16x16x32_bf16 v[26:29], v[180:183], v[212:215], v[26:29]
	v_mfma_f32_16x16x32_bf16 v[22:25], v[188:191], v[212:215], v[22:25]
	v_mfma_f32_16x16x32_bf16 v[10:13], v[180:183], v[220:223], v[10:13]
	v_mfma_f32_16x16x32_bf16 v[2:5], v[188:191], v[220:223], v[2:5]
	s_setprio 0
	s_barrier
	s_add_i32 s85, 0, 0x18000
	s_add_i32 s88, 0, 0x1c000
	v_add_u32_e32 v154, s85, v165
	v_add_u32_e32 v167, s88, v165
	ds_read_b128 v[98:101], v154
	ds_read_b128 v[134:137], v154 offset:1024
	ds_read_b128 v[150:153], v154 offset:2048
	ds_read_b128 v[154:157], v154 offset:3072
	ds_read_b128 v[158:161], v167
	ds_read_b128 v[180:183], v167 offset:1024
	ds_read_b128 v[184:187], v167 offset:2048
	ds_read_b128 v[188:191], v167 offset:3072
	s_add_u32 s26, s26, 0x40000
	s_addc_u32 s27, s27, 0
	s_mov_b32 m0, s42
	v_lshl_add_u64 v[230:231], s[26:27], 0, v[144:145]
	ds_read_b128 v[192:195], v166 offset:32768
	ds_read_b128 v[196:199], v166 offset:33792
	ds_read_b128 v[200:203], v166 offset:34816
	ds_read_b128 v[204:207], v166 offset:35840
	ds_read_b128 v[208:211], v166 offset:36864
	ds_read_b128 v[212:215], v166 offset:37888
	ds_read_b128 v[216:219], v166 offset:38912
	ds_read_b128 v[220:223], v166 offset:39936
	global_load_lds_dwordx4 v[230:231], off
	v_lshl_add_u64 v[230:231], s[26:27], 0, v[140:141]
	s_mov_b32 m0, s43
	s_nop 0
	global_load_lds_dwordx4 v[230:231], off
	s_waitcnt vmcnt(8)
	s_waitcnt lgkmcnt(0)
	s_barrier
	s_setprio 1
	v_mfma_f32_16x16x32_bf16 v[130:133], v[98:101], v[192:195], v[130:133]
	v_mfma_f32_16x16x32_bf16 v[118:121], v[150:153], v[192:195], v[118:121]
	v_mfma_f32_16x16x32_bf16 v[114:117], v[98:101], v[200:203], v[114:117]
	v_mfma_f32_16x16x32_bf16 v[102:105], v[150:153], v[200:203], v[102:105]
	v_mfma_f32_16x16x32_bf16 v[94:97], v[98:101], v[208:211], v[94:97]
	v_mfma_f32_16x16x32_bf16 v[82:85], v[150:153], v[208:211], v[82:85]
	v_mfma_f32_16x16x32_bf16 v[78:81], v[98:101], v[216:219], v[78:81]
	v_mfma_f32_16x16x32_bf16 v[66:69], v[150:153], v[216:219], v[66:69]
	v_mfma_f32_16x16x32_bf16 v[130:133], v[134:137], v[196:199], v[130:133]
	v_mfma_f32_16x16x32_bf16 v[118:121], v[154:157], v[196:199], v[118:121]
	v_mfma_f32_16x16x32_bf16 v[114:117], v[134:137], v[204:207], v[114:117]
	v_mfma_f32_16x16x32_bf16 v[102:105], v[154:157], v[204:207], v[102:105]
	v_mfma_f32_16x16x32_bf16 v[94:97], v[134:137], v[212:215], v[94:97]
	v_mfma_f32_16x16x32_bf16 v[82:85], v[154:157], v[212:215], v[82:85]
	v_mfma_f32_16x16x32_bf16 v[78:81], v[134:137], v[220:223], v[78:81]
	v_mfma_f32_16x16x32_bf16 v[66:69], v[154:157], v[220:223], v[66:69]
	v_mfma_f32_16x16x32_bf16 v[126:129], v[158:161], v[192:195], v[126:129]
	v_mfma_f32_16x16x32_bf16 v[122:125], v[184:187], v[192:195], v[122:125]
	v_mfma_f32_16x16x32_bf16 v[110:113], v[158:161], v[200:203], v[110:113]
	v_mfma_f32_16x16x32_bf16 v[106:109], v[184:187], v[200:203], v[106:109]
	v_mfma_f32_16x16x32_bf16 v[90:93], v[158:161], v[208:211], v[90:93]
	v_mfma_f32_16x16x32_bf16 v[86:89], v[184:187], v[208:211], v[86:89]
	v_mfma_f32_16x16x32_bf16 v[74:77], v[158:161], v[216:219], v[74:77]
	v_mfma_f32_16x16x32_bf16 v[70:73], v[184:187], v[216:219], v[70:73]
	v_mfma_f32_16x16x32_bf16 v[126:129], v[180:183], v[196:199], v[126:129]
	v_mfma_f32_16x16x32_bf16 v[122:125], v[188:191], v[196:199], v[122:125]
	v_mfma_f32_16x16x32_bf16 v[110:113], v[180:183], v[204:207], v[110:113]
	v_mfma_f32_16x16x32_bf16 v[106:109], v[188:191], v[204:207], v[106:109]
	v_mfma_f32_16x16x32_bf16 v[90:93], v[180:183], v[212:215], v[90:93]
	v_mfma_f32_16x16x32_bf16 v[86:89], v[188:191], v[212:215], v[86:89]
	v_mfma_f32_16x16x32_bf16 v[74:77], v[180:183], v[220:223], v[74:77]
	v_mfma_f32_16x16x32_bf16 v[70:73], v[188:191], v[220:223], v[70:73]
	s_setprio 0
	s_barrier
; #define PG8_STAGE(bufoff, gbase, voff) do { _Pragma("unroll") for (int _i = 0; _i < 2; ++_i) \
;         __builtin_amdgcn_global_load_lds((const unsigned*)((const char*)(gbase) + (voff)[_i]), (LAS unsigned*)(lds + (bufoff) + ldsw + _i * 8192), 16, 0, 0); } while (0)
; #define PG8_LDA(dst, b, h) do { _Pragma("unroll") for (int m = 0; m < 4; ++m) _Pragma("unroll") for (int k = 0; k < 2; ++k) dst[m][k] = *(const LAS bf16x8*)(lds + PG8_SA(b, h) + aoff + m * 2048 + k * 1024); } while (0)
; #define PG8_MMA(ai, bj, At, Bt) do { __builtin_amdgcn_s_setprio(1); _Pragma("unroll") for (int m = 0; m < 4; ++m) _Pragma("unroll") for (int n = 0; n < 2; ++n) _Pragma("unroll") for (int k = 0; k < 2; ++k) \
;         acc[ai][bj][m][n] = __builtin_amdgcn_mfma_f32_16x16x32_bf16(Bt[n][k], At[m][k], acc[ai][bj][m][n], 0, 0, 0); __builtin_amdgcn_s_setprio(0); } while (0)
; #define PG8_WAIT_V(n) asm volatile("s_waitcnt vmcnt(" #n ")" ::: "memory")
; #define PG8_WAIT_L(n) asm volatile("s_waitcnt lgkmcnt(" #n ")" ::: "memory")
; #define PG8_BAR __builtin_amdgcn_s_barrier()
; #define PG8_SCHED __builtin_amdgcn_sched_barrier(0)
; template <class Epi, class Sched>
; __device__ __forceinline__ void gemm_phase(LAS unsigned char* lds, const Gemm g, const Sched S, const Epi E, const int tid) {
;     ...
;             PG8_LDA(At, 1, 1); PG8_STAGE(PG8_SB(1, 0), b3, voffB); PG8_STAGE(PG8_SB(1, 1), b3 + hstepB, voffB); PG8_STAGE(PG8_SA(1, 0), a3, voffA);
;             PG8_WAIT_V(8); PG8_WAIT_L(0); PG8_BAR; PG8_MMA(1, 0, At, B0); PG8_MMA(1, 1, At, B1); PG8_BAR; PG8_SCHED;
;         }
;         if (wr == 0) PG8_BAR;
	s_add_i32 s26, s85, s28
	v_lshl_add_u64 v[162:163], v[162:163], 0, s[64:65]
	s_mov_b32 m0, s26
	ds_read_b128 v[192:195], v166 offset:49152
	ds_read_b128 v[196:199], v166 offset:50176
	ds_read_b128 v[200:203], v166 offset:51200
	ds_read_b128 v[204:207], v166 offset:52224
	ds_read_b128 v[208:211], v166 offset:53248
	ds_read_b128 v[212:215], v166 offset:54272
	ds_read_b128 v[216:219], v166 offset:55296
	ds_read_b128 v[220:223], v166 offset:56320
	global_load_lds_dwordx4 v[162:163], off
	s_add_i32 m0, s26, 0x2000
	s_add_u32 s24, s24, 0x40080
	v_lshl_add_u64 v[162:163], v[224:225], 0, s[64:65]
	s_addc_u32 s25, s25, 0
	s_add_i32 s26, s88, s28
	global_load_lds_dwordx4 v[162:163], off
	v_lshl_add_u64 v[162:163], s[24:25], 0, v[142:143]
	s_mov_b32 m0, s26
	s_nop 0
	global_load_lds_dwordx4 v[162:163], off
	v_lshl_add_u64 v[162:163], s[24:25], 0, v[138:139]
	s_add_i32 m0, s26, 0x2000
	s_nop 0
	global_load_lds_dwordx4 v[162:163], off
	v_lshl_add_u64 v[162:163], v[226:227], 0, s[64:65]
	s_mov_b32 m0, s46
	s_nop 0
	global_load_lds_dwordx4 v[162:163], off
	v_lshl_add_u64 v[162:163], v[228:229], 0, s[64:65]
	s_mov_b32 m0, s47
	s_nop 0
	global_load_lds_dwordx4 v[162:163], off
	s_waitcnt vmcnt(8)
	s_waitcnt lgkmcnt(0)
	s_barrier
	s_setprio 1
	v_mfma_f32_16x16x32_bf16 v[62:65], v[98:101], v[192:195], v[62:65]
	v_mfma_f32_16x16x32_bf16 v[50:53], v[150:153], v[192:195], v[50:53]
	v_mfma_f32_16x16x32_bf16 v[46:49], v[98:101], v[200:203], v[46:49]
	v_mfma_f32_16x16x32_bf16 v[34:37], v[150:153], v[200:203], v[34:37]
	v_mfma_f32_16x16x32_bf16 v[30:33], v[98:101], v[208:211], v[30:33]
	v_mfma_f32_16x16x32_bf16 v[18:21], v[150:153], v[208:211], v[18:21]
	v_mfma_f32_16x16x32_bf16 v[14:17], v[98:101], v[216:219], v[14:17]
	v_mfma_f32_16x16x32_bf16 v[6:9], v[150:153], v[216:219], v[6:9]
	v_mfma_f32_16x16x32_bf16 v[62:65], v[134:137], v[196:199], v[62:65]
	v_mfma_f32_16x16x32_bf16 v[50:53], v[154:157], v[196:199], v[50:53]
	v_mfma_f32_16x16x32_bf16 v[46:49], v[134:137], v[204:207], v[46:49]
	v_mfma_f32_16x16x32_bf16 v[34:37], v[154:157], v[204:207], v[34:37]
	v_mfma_f32_16x16x32_bf16 v[30:33], v[134:137], v[212:215], v[30:33]
	v_mfma_f32_16x16x32_bf16 v[18:21], v[154:157], v[212:215], v[18:21]
	v_mfma_f32_16x16x32_bf16 v[14:17], v[134:137], v[220:223], v[14:17]
	v_mfma_f32_16x16x32_bf16 v[6:9], v[154:157], v[220:223], v[6:9]
	v_mfma_f32_16x16x32_bf16 v[58:61], v[158:161], v[192:195], v[58:61]
	v_mfma_f32_16x16x32_bf16 v[54:57], v[184:187], v[192:195], v[54:57]
	v_mfma_f32_16x16x32_bf16 v[42:45], v[158:161], v[200:203], v[42:45]
	v_mfma_f32_16x16x32_bf16 v[38:41], v[184:187], v[200:203], v[38:41]
	v_mfma_f32_16x16x32_bf16 v[26:29], v[158:161], v[208:211], v[26:29]
	v_mfma_f32_16x16x32_bf16 v[22:25], v[184:187], v[208:211], v[22:25]
	v_mfma_f32_16x16x32_bf16 v[10:13], v[158:161], v[216:219], v[10:13]
	v_mfma_f32_16x16x32_bf16 v[2:5], v[184:187], v[216:219], v[2:5]
	v_mfma_f32_16x16x32_bf16 v[58:61], v[180:183], v[196:199], v[58:61]
	v_mfma_f32_16x16x32_bf16 v[54:57], v[188:191], v[196:199], v[54:57]
	v_mfma_f32_16x16x32_bf16 v[42:45], v[180:183], v[204:207], v[42:45]
	v_mfma_f32_16x16x32_bf16 v[38:41], v[188:191], v[204:207], v[38:41]
	v_mfma_f32_16x16x32_bf16 v[26:29], v[180:183], v[212:215], v[26:29]
	v_mfma_f32_16x16x32_bf16 v[22:25], v[188:191], v[212:215], v[22:25]
	v_mfma_f32_16x16x32_bf16 v[10:13], v[180:183], v[220:223], v[10:13]
	v_mfma_f32_16x16x32_bf16 v[2:5], v[188:191], v[220:223], v[2:5]
	s_setprio 0
	s_barrier
	s_add_i32 s84, s84, 2
	s_add_u32 s82, s82, 0x100
	s_addc_u32 s83, s83, 0
	s_add_u32 s22, s22, 0x100
	s_addc_u32 s23, s23, 0
	s_cmp_gt_u32 s84, 13
	s_cbranch_scc0 .LBB0_819
	s_and_b64 vcc, exec, s[12:13]
	s_cbranch_vccz .LBB0_822
	s_barrier
